# GEMM K-loops: LDS-DMA staging rebalanced from 2/6/2/6 to 4/4/4/4 pieces per phase (A halves in SP1, B halves in SP2; SP2 waits vmcnt(6)), on top of the attention reschedule
# speedup vs baseline: 1.0082x; 1.0082x over previous
; #define PG8_STAGE(bufoff, gbase, voff) do { _Pragma("unroll") for (int _i = 0; _i < 2; ++_i) { \
;         const unsigned m0v_ = (unsigned)(uintptr_t)(lds + (bufoff) + ldsw + _i * 8192); \
;         asm volatile("s_mov_b32 m0, %0\n\ts_nop 0\n\tglobal_load_lds_dwordx4 %1, %2\n\ts_nop 1" :: "s"(m0v_), "v"((voff)[_i]), "s"((const char*)(gbase)) : "m0", "memory"); } } while (0)
; #define PG8_LDA(dst, b, h) do { _Pragma("unroll") for (int m = 0; m < 4; ++m) _Pragma("unroll") for (int k = 0; k < 2; ++k) dst[m][k] = *(const LAS bf16x8*)(lds + PG8_SA(b, h) + aoff + m * 2048 + k * 1024); } while (0)
; #define PG8_LDB(dst, b, h) do { _Pragma("unroll") for (int n = 0; n < 2; ++n) _Pragma("unroll") for (int k = 0; k < 2; ++k) dst[n][k] = *(const LAS bf16x8*)(lds + PG8_SB(b, h) + boff + n * 2048 + k * 1024); } while (0)
; #define PG8_MMA(ai, bj, At, Bt) do { _Pragma("unroll") for (int m = 0; m < 4; ++m) _Pragma("unroll") for (int n = 0; n < 2; ++n) _Pragma("unroll") for (int k = 0; k < 2; ++k) \
;         acc[ai][bj][m][n] = __builtin_amdgcn_mfma_f32_16x16x32_bf16(Bt[n][k], At[m][k], acc[ai][bj][m][n], 0, 0, 0); } while (0)
; #define PG8_WAIT_V(n) asm volatile("s_waitcnt vmcnt(" #n ")" ::: "memory")
; #define PG8_WAIT_L(n) asm volatile("s_waitcnt lgkmcnt(" #n ")" ::: "memory")
; #define PG8_BAR __builtin_amdgcn_s_barrier()
; #define PG8_SCHED __builtin_amdgcn_sched_barrier(0)
; template <class Prob, class Epi, class Sched>
; __device__ __forceinline__ void gemm_phase(LAS unsigned char* lds, const Prob& P, const Sched& S, const Epi& E) {
;     ...
;             PG8_LDB(B0, 0, 0); PG8_LDB(B1, 0, 1); PG8_SCHED; PG8_LDA(At, 0, 0); PG8_STAGE(PG8_SA(1, 1), a1 + hstepA, voffA);
;             PG8_WAIT_V(8); PG8_WAIT_L(0); PG8_BAR; __builtin_amdgcn_s_setprio(1); PG8_MMA(0, 0, At, B0); PG8_MMA(0, 1, At, B1); __builtin_amdgcn_s_setprio(0); PG8_BAR; PG8_SCHED;
;             PG8_LDA(At, 0, 1); PG8_STAGE(PG8_SB(0, 0), b2, voffB); PG8_STAGE(PG8_SB(0, 1), b2 + hstepB, voffB); PG8_STAGE(PG8_SA(0, 0), a2, voffA);
.LBB0_270:
	ds_read_b128 v[136:139], v163
	ds_read_b128 v[140:143], v163 offset:1024
	ds_read_b128 v[144:147], v163 offset:2048
	ds_read_b128 v[148:151], v163 offset:3072
	s_waitcnt vmcnt(0)
	ds_read_b128 v[152:155], v164
	ds_read_b128 v[156:159], v164 offset:1024
	ds_read_b128 v[170:173], v164 offset:2048
	ds_read_b128 v[174:177], v164 offset:3072
	s_cmp_eq_u32 s71, 28
	s_cselect_b32 s68, s46, s15
	s_cselect_b32 s69, s47, s43
	s_cselect_b32 s54, s48, s45
	s_cselect_b32 s55, s49, s70
	s_add_u32 s6, s68, 0x80
	s_addc_u32 s7, s69, 0
	ds_read_b128 v[178:181], v165
	ds_read_b128 v[182:185], v165 offset:1024
	ds_read_b128 v[186:189], v165 offset:2048
	ds_read_b128 v[190:193], v165 offset:3072
	ds_read_b128 v[194:197], v165 offset:4096
	ds_read_b128 v[198:201], v165 offset:5120
	ds_read_b128 v[202:205], v165 offset:6144
	ds_read_b128 v[206:209], v165 offset:7168
	s_sub_u32 s98, s4, 0x80000
	s_subb_u32 s99, s5, 0
	s_mov_b32 m0, s72
	s_nop 0
	global_load_lds_dwordx4 v1, s[98:99]
	s_nop 1
	s_nop 0
	s_mov_b32 m0, s73
	s_nop 0
	global_load_lds_dwordx4 v161, s[98:99]
	s_nop 1
	s_mov_b32 m0, s76
	s_nop 0
	global_load_lds_dwordx4 v1, s[4:5]
	s_nop 1
	s_nop 0
	s_mov_b32 m0, s77
	s_nop 0
	global_load_lds_dwordx4 v161, s[4:5]
	s_nop 1
	s_waitcnt vmcnt(8)
	s_waitcnt lgkmcnt(0)
	s_barrier
	s_setprio 1
	s_waitcnt lgkmcnt(7)
	v_mfma_f32_16x16x32_bf16 v[126:129], v[136:139], v[178:181], v[126:129]
	v_mfma_f32_16x16x32_bf16 v[122:125], v[144:147], v[178:181], v[122:125]
	s_waitcnt lgkmcnt(5)
	v_mfma_f32_16x16x32_bf16 v[110:113], v[136:139], v[186:189], v[110:113]
	v_mfma_f32_16x16x32_bf16 v[106:109], v[144:147], v[186:189], v[106:109]
	s_waitcnt lgkmcnt(3)
	v_mfma_f32_16x16x32_bf16 v[94:97], v[136:139], v[194:197], v[94:97]
	v_mfma_f32_16x16x32_bf16 v[90:93], v[144:147], v[194:197], v[90:93]
	s_waitcnt lgkmcnt(1)
	v_mfma_f32_16x16x32_bf16 v[78:81], v[136:139], v[202:205], v[78:81]
	v_mfma_f32_16x16x32_bf16 v[74:77], v[144:147], v[202:205], v[74:77]
	v_mfma_f32_16x16x32_bf16 v[118:121], v[152:155], v[178:181], v[118:121]
	v_mfma_f32_16x16x32_bf16 v[114:117], v[170:173], v[178:181], v[114:117]
	v_mfma_f32_16x16x32_bf16 v[102:105], v[152:155], v[186:189], v[102:105]
	v_mfma_f32_16x16x32_bf16 v[98:101], v[170:173], v[186:189], v[98:101]
	v_mfma_f32_16x16x32_bf16 v[86:89], v[152:155], v[194:197], v[86:89]
	v_mfma_f32_16x16x32_bf16 v[82:85], v[170:173], v[194:197], v[82:85]
	v_mfma_f32_16x16x32_bf16 v[70:73], v[152:155], v[202:205], v[70:73]
	v_mfma_f32_16x16x32_bf16 v[66:69], v[170:173], v[202:205], v[66:69]
	v_mfma_f32_16x16x32_bf16 v[126:129], v[140:143], v[182:185], v[126:129]
	v_mfma_f32_16x16x32_bf16 v[122:125], v[148:151], v[182:185], v[122:125]
	v_mfma_f32_16x16x32_bf16 v[110:113], v[140:143], v[190:193], v[110:113]
	v_mfma_f32_16x16x32_bf16 v[106:109], v[148:151], v[190:193], v[106:109]
	v_mfma_f32_16x16x32_bf16 v[94:97], v[140:143], v[198:201], v[94:97]
	v_mfma_f32_16x16x32_bf16 v[90:93], v[148:151], v[198:201], v[90:93]
	s_waitcnt lgkmcnt(0)
	v_mfma_f32_16x16x32_bf16 v[78:81], v[140:143], v[206:209], v[78:81]
	v_mfma_f32_16x16x32_bf16 v[74:77], v[148:151], v[206:209], v[74:77]
	v_mfma_f32_16x16x32_bf16 v[118:121], v[156:159], v[182:185], v[118:121]
	v_mfma_f32_16x16x32_bf16 v[114:117], v[174:177], v[182:185], v[114:117]
	v_mfma_f32_16x16x32_bf16 v[102:105], v[156:159], v[190:193], v[102:105]
	v_mfma_f32_16x16x32_bf16 v[98:101], v[174:177], v[190:193], v[98:101]
	v_mfma_f32_16x16x32_bf16 v[86:89], v[156:159], v[198:201], v[86:89]
	v_mfma_f32_16x16x32_bf16 v[82:85], v[174:177], v[198:201], v[82:85]
	v_mfma_f32_16x16x32_bf16 v[70:73], v[156:159], v[206:209], v[70:73]
	v_mfma_f32_16x16x32_bf16 v[66:69], v[174:177], v[206:209], v[66:69]
	s_setprio 0
	s_barrier
	ds_read_b128 v[178:181], v165 offset:16384
	ds_read_b128 v[182:185], v165 offset:17408
	ds_read_b128 v[186:189], v165 offset:18432
	ds_read_b128 v[190:193], v165 offset:19456
	ds_read_b128 v[194:197], v165 offset:20480
	ds_read_b128 v[198:201], v165 offset:21504
	ds_read_b128 v[202:205], v165 offset:22528
	ds_read_b128 v[206:209], v165 offset:23552
	s_mov_b32 m0, s34
	s_nop 0
	global_load_lds_dwordx4 v160, s[54:55]
	s_nop 1
	s_add_u32 s82, s54, 0x80000
	s_mov_b32 m0, s35
	s_nop 0
	global_load_lds_dwordx4 v162, s[54:55]
	s_nop 1
	s_addc_u32 s83, s55, 0
	s_mov_b32 m0, s53
	s_nop 0
	global_load_lds_dwordx4 v160, s[82:83]
	s_nop 1
	s_nop 0
	s_mov_b32 m0, s56
	s_nop 0
	global_load_lds_dwordx4 v162, s[82:83]
	s_nop 1
	s_nop 0
	s_waitcnt vmcnt(6)
	s_waitcnt lgkmcnt(0)
	s_barrier
; #define PG8_STAGE(bufoff, gbase, voff) do { _Pragma("unroll") for (int _i = 0; _i < 2; ++_i) { \
;         const unsigned m0v_ = (unsigned)(uintptr_t)(lds + (bufoff) + ldsw + _i * 8192); \
;         asm volatile("s_mov_b32 m0, %0\n\ts_nop 0\n\tglobal_load_lds_dwordx4 %1, %2\n\ts_nop 1" :: "s"(m0v_), "v"((voff)[_i]), "s"((const char*)(gbase)) : "m0", "memory"); } } while (0)
; #define PG8_LDA(dst, b, h) do { _Pragma("unroll") for (int m = 0; m < 4; ++m) _Pragma("unroll") for (int k = 0; k < 2; ++k) dst[m][k] = *(const LAS bf16x8*)(lds + PG8_SA(b, h) + aoff + m * 2048 + k * 1024); } while (0)
; #define PG8_LDB(dst, b, h) do { _Pragma("unroll") for (int n = 0; n < 2; ++n) _Pragma("unroll") for (int k = 0; k < 2; ++k) dst[n][k] = *(const LAS bf16x8*)(lds + PG8_SB(b, h) + boff + n * 2048 + k * 1024); } while (0)
; #define PG8_MMA(ai, bj, At, Bt) do { _Pragma("unroll") for (int m = 0; m < 4; ++m) _Pragma("unroll") for (int n = 0; n < 2; ++n) _Pragma("unroll") for (int k = 0; k < 2; ++k) \
;         acc[ai][bj][m][n] = __builtin_amdgcn_mfma_f32_16x16x32_bf16(Bt[n][k], At[m][k], acc[ai][bj][m][n], 0, 0, 0); } while (0)
; #define PG8_WAIT_V(n) asm volatile("s_waitcnt vmcnt(" #n ")" ::: "memory")
; #define PG8_BAR __builtin_amdgcn_s_barrier()
; template <class Prob, class Epi, class Sched>
; __device__ __forceinline__ void gemm_phase(LAS unsigned char* lds, const Prob& P, const Sched& S, const Epi& E) {
;     ...
;             PG8_LDA(At, 0, 1); PG8_STAGE(PG8_SB(0, 0), b2, voffB); PG8_STAGE(PG8_SB(0, 1), b2 + hstepB, voffB); PG8_STAGE(PG8_SA(0, 0), a2, voffA);
;             PG8_WAIT_V(8); PG8_WAIT_L(0); PG8_BAR; __builtin_amdgcn_s_setprio(1); PG8_MMA(1, 0, At, B0); PG8_MMA(1, 1, At, B1); __builtin_amdgcn_s_setprio(0); PG8_BAR; PG8_SCHED;
;             PG8_LDB(B0, 1, 0); PG8_LDB(B1, 1, 1); PG8_SCHED; PG8_LDA(At, 1, 0); PG8_STAGE(PG8_SA(0, 1), a2 + hstepA, voffA);
;             PG8_WAIT_V(8); PG8_WAIT_L(0); PG8_BAR; __builtin_amdgcn_s_setprio(1); PG8_MMA(0, 0, At, B0); PG8_MMA(0, 1, At, B1); __builtin_amdgcn_s_setprio(0); PG8_BAR; PG8_SCHED;
;             PG8_LDA(At, 1, 1); PG8_STAGE(PG8_SB(1, 0), b3, voffB); PG8_STAGE(PG8_SB(1, 1), b3 + hstepB, voffB); PG8_STAGE(PG8_SA(1, 0), a3, voffA);
;             PG8_WAIT_V(8); PG8_WAIT_L(0); PG8_BAR; __builtin_amdgcn_s_setprio(1); PG8_MMA(1, 0, At, B0); PG8_MMA(1, 1, At, B1); __builtin_amdgcn_s_setprio(0); PG8_BAR; PG8_SCHED;
	s_setprio 1
	s_waitcnt lgkmcnt(7)
	v_mfma_f32_16x16x32_bf16 v[62:65], v[136:139], v[178:181], v[62:65]
	v_mfma_f32_16x16x32_bf16 v[58:61], v[144:147], v[178:181], v[58:61]
	s_waitcnt lgkmcnt(5)
	v_mfma_f32_16x16x32_bf16 v[46:49], v[136:139], v[186:189], v[46:49]
	v_mfma_f32_16x16x32_bf16 v[42:45], v[144:147], v[186:189], v[42:45]
	s_waitcnt lgkmcnt(3)
	v_mfma_f32_16x16x32_bf16 v[30:33], v[136:139], v[194:197], v[30:33]
	v_mfma_f32_16x16x32_bf16 v[26:29], v[144:147], v[194:197], v[26:29]
	s_waitcnt lgkmcnt(1)
	v_mfma_f32_16x16x32_bf16 v[14:17], v[136:139], v[202:205], v[14:17]
	v_mfma_f32_16x16x32_bf16 v[10:13], v[144:147], v[202:205], v[10:13]
	v_mfma_f32_16x16x32_bf16 v[54:57], v[152:155], v[178:181], v[54:57]
	v_mfma_f32_16x16x32_bf16 v[50:53], v[170:173], v[178:181], v[50:53]
	v_mfma_f32_16x16x32_bf16 v[38:41], v[152:155], v[186:189], v[38:41]
	v_mfma_f32_16x16x32_bf16 v[34:37], v[170:173], v[186:189], v[34:37]
	v_mfma_f32_16x16x32_bf16 v[22:25], v[152:155], v[194:197], v[22:25]
	v_mfma_f32_16x16x32_bf16 v[18:21], v[170:173], v[194:197], v[18:21]
	v_mfma_f32_16x16x32_bf16 v[6:9], v[152:155], v[202:205], v[6:9]
	v_mfma_f32_16x16x32_bf16 v[2:5], v[170:173], v[202:205], v[2:5]
	v_mfma_f32_16x16x32_bf16 v[62:65], v[140:143], v[182:185], v[62:65]
	v_mfma_f32_16x16x32_bf16 v[58:61], v[148:151], v[182:185], v[58:61]
	v_mfma_f32_16x16x32_bf16 v[46:49], v[140:143], v[190:193], v[46:49]
	v_mfma_f32_16x16x32_bf16 v[42:45], v[148:151], v[190:193], v[42:45]
	v_mfma_f32_16x16x32_bf16 v[30:33], v[140:143], v[198:201], v[30:33]
	v_mfma_f32_16x16x32_bf16 v[26:29], v[148:151], v[198:201], v[26:29]
	s_waitcnt lgkmcnt(0)
	v_mfma_f32_16x16x32_bf16 v[14:17], v[140:143], v[206:209], v[14:17]
	v_mfma_f32_16x16x32_bf16 v[10:13], v[148:151], v[206:209], v[10:13]
	v_mfma_f32_16x16x32_bf16 v[54:57], v[156:159], v[182:185], v[54:57]
	v_mfma_f32_16x16x32_bf16 v[50:53], v[174:177], v[182:185], v[50:53]
	v_mfma_f32_16x16x32_bf16 v[38:41], v[156:159], v[190:193], v[38:41]
	v_mfma_f32_16x16x32_bf16 v[34:37], v[174:177], v[190:193], v[34:37]
	v_mfma_f32_16x16x32_bf16 v[22:25], v[156:159], v[198:201], v[22:25]
	v_mfma_f32_16x16x32_bf16 v[18:21], v[174:177], v[198:201], v[18:21]
	v_mfma_f32_16x16x32_bf16 v[6:9], v[156:159], v[206:209], v[6:9]
	v_mfma_f32_16x16x32_bf16 v[2:5], v[174:177], v[206:209], v[2:5]
	s_setprio 0
	s_barrier
	ds_read_b128 v[136:139], v166
	ds_read_b128 v[140:143], v166 offset:1024
	ds_read_b128 v[144:147], v166 offset:2048
	ds_read_b128 v[148:151], v166 offset:3072
	ds_read_b128 v[152:155], v167
	ds_read_b128 v[156:159], v167 offset:1024
	ds_read_b128 v[170:173], v167 offset:2048
	ds_read_b128 v[174:177], v167 offset:3072
	ds_read_b128 v[178:181], v165 offset:32768
	ds_read_b128 v[182:185], v165 offset:33792
	ds_read_b128 v[186:189], v165 offset:34816
	ds_read_b128 v[190:193], v165 offset:35840
	ds_read_b128 v[194:197], v165 offset:36864
	ds_read_b128 v[198:201], v165 offset:37888
	ds_read_b128 v[202:205], v165 offset:38912
	ds_read_b128 v[206:209], v165 offset:39936
	s_mov_b32 m0, s3
	s_nop 0
	global_load_lds_dwordx4 v1, s[68:69]
	s_nop 1
	s_nop 0
	s_mov_b32 m0, s57
	s_nop 0
	global_load_lds_dwordx4 v161, s[68:69]
	s_nop 1
	s_add_u32 s68, s68, 0x80000
	s_addc_u32 s69, s69, 0
	s_mov_b32 m0, s58
	s_nop 0
	global_load_lds_dwordx4 v1, s[68:69]
	s_nop 1
	s_nop 0
	s_mov_b32 m0, s59
	s_nop 0
	global_load_lds_dwordx4 v161, s[68:69]
	s_nop 1
	s_waitcnt vmcnt(8)
	s_waitcnt lgkmcnt(0)
	s_barrier
	s_setprio 1
	s_waitcnt lgkmcnt(7)
	v_mfma_f32_16x16x32_bf16 v[126:129], v[136:139], v[178:181], v[126:129]
	v_mfma_f32_16x16x32_bf16 v[122:125], v[144:147], v[178:181], v[122:125]
	s_waitcnt lgkmcnt(5)
	v_mfma_f32_16x16x32_bf16 v[110:113], v[136:139], v[186:189], v[110:113]
	v_mfma_f32_16x16x32_bf16 v[106:109], v[144:147], v[186:189], v[106:109]
	s_waitcnt lgkmcnt(3)
	v_mfma_f32_16x16x32_bf16 v[94:97], v[136:139], v[194:197], v[94:97]
	v_mfma_f32_16x16x32_bf16 v[90:93], v[144:147], v[194:197], v[90:93]
	s_waitcnt lgkmcnt(1)
	v_mfma_f32_16x16x32_bf16 v[78:81], v[136:139], v[202:205], v[78:81]
	v_mfma_f32_16x16x32_bf16 v[74:77], v[144:147], v[202:205], v[74:77]
	v_mfma_f32_16x16x32_bf16 v[118:121], v[152:155], v[178:181], v[118:121]
	v_mfma_f32_16x16x32_bf16 v[114:117], v[170:173], v[178:181], v[114:117]
	v_mfma_f32_16x16x32_bf16 v[102:105], v[152:155], v[186:189], v[102:105]
	v_mfma_f32_16x16x32_bf16 v[98:101], v[170:173], v[186:189], v[98:101]
	v_mfma_f32_16x16x32_bf16 v[86:89], v[152:155], v[194:197], v[86:89]
	v_mfma_f32_16x16x32_bf16 v[82:85], v[170:173], v[194:197], v[82:85]
	v_mfma_f32_16x16x32_bf16 v[70:73], v[152:155], v[202:205], v[70:73]
	v_mfma_f32_16x16x32_bf16 v[66:69], v[170:173], v[202:205], v[66:69]
	v_mfma_f32_16x16x32_bf16 v[126:129], v[140:143], v[182:185], v[126:129]
	v_mfma_f32_16x16x32_bf16 v[122:125], v[148:151], v[182:185], v[122:125]
	v_mfma_f32_16x16x32_bf16 v[110:113], v[140:143], v[190:193], v[110:113]
	v_mfma_f32_16x16x32_bf16 v[106:109], v[148:151], v[190:193], v[106:109]
	v_mfma_f32_16x16x32_bf16 v[94:97], v[140:143], v[198:201], v[94:97]
	v_mfma_f32_16x16x32_bf16 v[90:93], v[148:151], v[198:201], v[90:93]
	s_waitcnt lgkmcnt(0)
	v_mfma_f32_16x16x32_bf16 v[78:81], v[140:143], v[206:209], v[78:81]
	v_mfma_f32_16x16x32_bf16 v[74:77], v[148:151], v[206:209], v[74:77]
	v_mfma_f32_16x16x32_bf16 v[118:121], v[156:159], v[182:185], v[118:121]
	v_mfma_f32_16x16x32_bf16 v[114:117], v[174:177], v[182:185], v[114:117]
	v_mfma_f32_16x16x32_bf16 v[102:105], v[156:159], v[190:193], v[102:105]
	v_mfma_f32_16x16x32_bf16 v[98:101], v[174:177], v[190:193], v[98:101]
	v_mfma_f32_16x16x32_bf16 v[86:89], v[156:159], v[198:201], v[86:89]
	v_mfma_f32_16x16x32_bf16 v[82:85], v[174:177], v[198:201], v[82:85]
	v_mfma_f32_16x16x32_bf16 v[70:73], v[156:159], v[206:209], v[70:73]
	v_mfma_f32_16x16x32_bf16 v[66:69], v[174:177], v[206:209], v[66:69]
	s_setprio 0
	s_barrier
; #define PG8_STAGE(bufoff, gbase, voff) do { _Pragma("unroll") for (int _i = 0; _i < 2; ++_i) { \
;         const unsigned m0v_ = (unsigned)(uintptr_t)(lds + (bufoff) + ldsw + _i * 8192); \
;         asm volatile("s_mov_b32 m0, %0\n\ts_nop 0\n\tglobal_load_lds_dwordx4 %1, %2\n\ts_nop 1" :: "s"(m0v_), "v"((voff)[_i]), "s"((const char*)(gbase)) : "m0", "memory"); } } while (0)
; #define PG8_LDA(dst, b, h) do { _Pragma("unroll") for (int m = 0; m < 4; ++m) _Pragma("unroll") for (int k = 0; k < 2; ++k) dst[m][k] = *(const LAS bf16x8*)(lds + PG8_SA(b, h) + aoff + m * 2048 + k * 1024); } while (0)
; #define PG8_MMA(ai, bj, At, Bt) do { _Pragma("unroll") for (int m = 0; m < 4; ++m) _Pragma("unroll") for (int n = 0; n < 2; ++n) _Pragma("unroll") for (int k = 0; k < 2; ++k) \
;         acc[ai][bj][m][n] = __builtin_amdgcn_mfma_f32_16x16x32_bf16(Bt[n][k], At[m][k], acc[ai][bj][m][n], 0, 0, 0); } while (0)
; #define PG8_WAIT_V(n) asm volatile("s_waitcnt vmcnt(" #n ")" ::: "memory")
; #define PG8_WAIT_L(n) asm volatile("s_waitcnt lgkmcnt(" #n ")" ::: "memory")
; #define PG8_BAR __builtin_amdgcn_s_barrier()
; #define PG8_SCHED __builtin_amdgcn_sched_barrier(0)
; template <class Prob, class Epi, class Sched>
; __device__ __forceinline__ void gemm_phase(LAS unsigned char* lds, const Prob& P, const Sched& S, const Epi& E) {
;     ...
;             PG8_LDA(At, 1, 1); PG8_STAGE(PG8_SB(1, 0), b3, voffB); PG8_STAGE(PG8_SB(1, 1), b3 + hstepB, voffB); PG8_STAGE(PG8_SA(1, 0), a3, voffA);
;             PG8_WAIT_V(8); PG8_WAIT_L(0); PG8_BAR; __builtin_amdgcn_s_setprio(1); PG8_MMA(1, 0, At, B0); PG8_MMA(1, 1, At, B1); __builtin_amdgcn_s_setprio(0); PG8_BAR; PG8_SCHED;
;         }
;         if (wr == 0) PG8_BAR;
	ds_read_b128 v[178:181], v165 offset:49152
	ds_read_b128 v[182:185], v165 offset:50176
	ds_read_b128 v[186:189], v165 offset:51200
	ds_read_b128 v[190:193], v165 offset:52224
	ds_read_b128 v[194:197], v165 offset:53248
	ds_read_b128 v[198:201], v165 offset:54272
	ds_read_b128 v[202:205], v165 offset:55296
	ds_read_b128 v[206:209], v165 offset:56320
	s_add_u32 s68, s54, 0x80
	s_addc_u32 s69, s55, 0
	s_mov_b32 m0, s64
	s_nop 0
	global_load_lds_dwordx4 v160, s[68:69]
	s_nop 1
	s_add_u32 s54, s54, 0x80080
	s_mov_b32 m0, s65
	s_nop 0
	global_load_lds_dwordx4 v162, s[68:69]
	s_nop 1
	s_addc_u32 s55, s55, 0
	s_mov_b32 m0, s74
	s_nop 0
	global_load_lds_dwordx4 v160, s[54:55]
	s_nop 1
	s_nop 0
	s_mov_b32 m0, s75
	s_nop 0
	global_load_lds_dwordx4 v162, s[54:55]
	s_nop 1
	s_nop 0
	s_waitcnt vmcnt(6)
	s_waitcnt lgkmcnt(0)
	s_barrier
	s_setprio 1
	s_waitcnt lgkmcnt(7)
	v_mfma_f32_16x16x32_bf16 v[62:65], v[136:139], v[178:181], v[62:65]
	v_mfma_f32_16x16x32_bf16 v[58:61], v[144:147], v[178:181], v[58:61]
	s_waitcnt lgkmcnt(5)
	v_mfma_f32_16x16x32_bf16 v[46:49], v[136:139], v[186:189], v[46:49]
	v_mfma_f32_16x16x32_bf16 v[42:45], v[144:147], v[186:189], v[42:45]
	s_waitcnt lgkmcnt(3)
	v_mfma_f32_16x16x32_bf16 v[30:33], v[136:139], v[194:197], v[30:33]
	v_mfma_f32_16x16x32_bf16 v[26:29], v[144:147], v[194:197], v[26:29]
	s_waitcnt lgkmcnt(1)
	v_mfma_f32_16x16x32_bf16 v[14:17], v[136:139], v[202:205], v[14:17]
	v_mfma_f32_16x16x32_bf16 v[10:13], v[144:147], v[202:205], v[10:13]
	v_mfma_f32_16x16x32_bf16 v[54:57], v[152:155], v[178:181], v[54:57]
	v_mfma_f32_16x16x32_bf16 v[50:53], v[170:173], v[178:181], v[50:53]
	v_mfma_f32_16x16x32_bf16 v[38:41], v[152:155], v[186:189], v[38:41]
	v_mfma_f32_16x16x32_bf16 v[34:37], v[170:173], v[186:189], v[34:37]
	v_mfma_f32_16x16x32_bf16 v[22:25], v[152:155], v[194:197], v[22:25]
	v_mfma_f32_16x16x32_bf16 v[18:21], v[170:173], v[194:197], v[18:21]
	v_mfma_f32_16x16x32_bf16 v[6:9], v[152:155], v[202:205], v[6:9]
	v_mfma_f32_16x16x32_bf16 v[2:5], v[170:173], v[202:205], v[2:5]
	v_mfma_f32_16x16x32_bf16 v[62:65], v[140:143], v[182:185], v[62:65]
	v_mfma_f32_16x16x32_bf16 v[58:61], v[148:151], v[182:185], v[58:61]
	v_mfma_f32_16x16x32_bf16 v[46:49], v[140:143], v[190:193], v[46:49]
	v_mfma_f32_16x16x32_bf16 v[42:45], v[148:151], v[190:193], v[42:45]
	v_mfma_f32_16x16x32_bf16 v[30:33], v[140:143], v[198:201], v[30:33]
	v_mfma_f32_16x16x32_bf16 v[26:29], v[148:151], v[198:201], v[26:29]
	s_waitcnt lgkmcnt(0)
	v_mfma_f32_16x16x32_bf16 v[14:17], v[140:143], v[206:209], v[14:17]
	v_mfma_f32_16x16x32_bf16 v[10:13], v[148:151], v[206:209], v[10:13]
	v_mfma_f32_16x16x32_bf16 v[54:57], v[156:159], v[182:185], v[54:57]
	v_mfma_f32_16x16x32_bf16 v[50:53], v[174:177], v[182:185], v[50:53]
	v_mfma_f32_16x16x32_bf16 v[38:41], v[156:159], v[190:193], v[38:41]
	v_mfma_f32_16x16x32_bf16 v[34:37], v[174:177], v[190:193], v[34:37]
	v_mfma_f32_16x16x32_bf16 v[22:25], v[156:159], v[198:201], v[22:25]
	v_mfma_f32_16x16x32_bf16 v[18:21], v[174:177], v[198:201], v[18:21]
	v_mfma_f32_16x16x32_bf16 v[6:9], v[156:159], v[206:209], v[6:9]
	v_mfma_f32_16x16x32_bf16 v[2:5], v[174:177], v[206:209], v[2:5]
	s_setprio 0
	s_barrier
	s_add_i32 s71, s71, 2
	s_add_u32 s15, s15, 0x100
	s_addc_u32 s43, s43, 0
	s_add_u32 s45, s45, 0x100
	s_addc_u32 s70, s70, 0
	s_add_u32 s4, s4, 0x100
	s_addc_u32 s5, s5, 0
	s_cmp_gt_u32 s71, 29
	s_cbranch_scc0 .LBB0_270
	s_and_b64 vcc, exec, s[40:41]
	s_cbranch_vccz .LBB0_273
	s_barrier

; #define PG8_STAGE(bufoff, gbase, voff) do { _Pragma("unroll") for (int _i = 0; _i < 2; ++_i) { \
;         const unsigned m0v_ = (unsigned)(uintptr_t)(lds + (bufoff) + ldsw + _i * 8192); \
;         asm volatile("s_mov_b32 m0, %0\n\ts_nop 0\n\tglobal_load_lds_dwordx4 %1, %2\n\ts_nop 1" :: "s"(m0v_), "v"((voff)[_i]), "s"((const char*)(gbase)) : "m0", "memory"); } } while (0)
; #define PG8_LDA(dst, b, h) do { _Pragma("unroll") for (int m = 0; m < 4; ++m) _Pragma("unroll") for (int k = 0; k < 2; ++k) dst[m][k] = *(const LAS bf16x8*)(lds + PG8_SA(b, h) + aoff + m * 2048 + k * 1024); } while (0)
; #define PG8_LDB(dst, b, h) do { _Pragma("unroll") for (int n = 0; n < 2; ++n) _Pragma("unroll") for (int k = 0; k < 2; ++k) dst[n][k] = *(const LAS bf16x8*)(lds + PG8_SB(b, h) + boff + n * 2048 + k * 1024); } while (0)
; #define PG8_MMA(ai, bj, At, Bt) do { _Pragma("unroll") for (int m = 0; m < 4; ++m) _Pragma("unroll") for (int n = 0; n < 2; ++n) _Pragma("unroll") for (int k = 0; k < 2; ++k) \
;         acc[ai][bj][m][n] = __builtin_amdgcn_mfma_f32_16x16x32_bf16(Bt[n][k], At[m][k], acc[ai][bj][m][n], 0, 0, 0); } while (0)
; #define PG8_WAIT_V(n) asm volatile("s_waitcnt vmcnt(" #n ")" ::: "memory")
; #define PG8_WAIT_L(n) asm volatile("s_waitcnt lgkmcnt(" #n ")" ::: "memory")
; template <class Prob, class Epi, class Sched>
; __device__ __forceinline__ void gemm_phase(LAS unsigned char* lds, const Prob& P, const Sched& S, const Epi& E) {
;     ...
;             const char* a1 = cA + (size_t)(t + 1) * kstep;
;             const char* a2 = last ? nA : cA + (size_t)(t + 2) * kstep; const char* b2 = last ? nB : cB + (size_t)(t + 2) * kstep;
;             const char* a3 = a2 + kstep; const char* b3 = b2 + kstep;
;             PG8_LDB(B0, 0, 0); PG8_LDB(B1, 0, 1); PG8_SCHED; PG8_LDA(At, 0, 0); PG8_STAGE(PG8_SA(1, 1), a1 + hstepA, voffA);
;             PG8_WAIT_V(8); PG8_WAIT_L(0); PG8_BAR; __builtin_amdgcn_s_setprio(1); PG8_MMA(0, 0, At, B0); PG8_MMA(0, 1, At, B1); __builtin_amdgcn_s_setprio(0); PG8_BAR; PG8_SCHED;
;             PG8_LDA(At, 0, 1); PG8_STAGE(PG8_SB(0, 0), b2, voffB); PG8_STAGE(PG8_SB(0, 1), b2 + hstepB, voffB); PG8_STAGE(PG8_SA(0, 0), a2, voffA);
;             PG8_WAIT_V(8); PG8_WAIT_L(0); PG8_BAR; __builtin_amdgcn_s_setprio(1); PG8_MMA(1, 0, At, B0); PG8_MMA(1, 1, At, B1); __builtin_amdgcn_s_setprio(0); PG8_BAR; PG8_SCHED;
.LBB0_451:
	v_add_u32_e32 v130, 0x10000, v219
	s_add_i32 s68, s6, 2
	ds_read_b128 v[132:135], v130
	s_waitcnt vmcnt(4)
	ds_read_b128 v[136:139], v130 offset:1024
	ds_read_b128 v[140:143], v130 offset:2048
	s_waitcnt vmcnt(3)
	ds_read_b128 v[144:147], v130 offset:3072
	v_add_u32_e32 v130, 0x14000, v219
	s_add_u32 s7, s78, s4
	s_waitcnt vmcnt(2)
	ds_read_b128 v[148:151], v130
	s_waitcnt vmcnt(0)
	ds_read_b128 v[152:155], v130 offset:1024
	ds_read_b128 v[156:159], v130 offset:2048
	ds_read_b128 v[160:163], v130 offset:3072
	s_addc_u32 s8, s79, s5
	s_add_u32 s9, s80, s4
	s_addc_u32 s74, s81, s5
	s_cmp_eq_u32 s55, s6
	s_cselect_b32 s10, s88, s7
	s_cselect_b32 s11, s89, s8
	s_cselect_b32 s8, s90, s9
	s_cselect_b32 s9, s91, s74
	s_add_u32 s6, s10, 0x80
	s_addc_u32 s7, s11, 0
	ds_read_b128 v[164:167], v220
	ds_read_b128 v[168:171], v220 offset:1024
	ds_read_b128 v[172:175], v220 offset:2048
	ds_read_b128 v[176:179], v220 offset:3072
	ds_read_b128 v[180:183], v220 offset:4096
	ds_read_b128 v[184:187], v220 offset:5120
	ds_read_b128 v[188:191], v220 offset:6144
	ds_read_b128 v[192:195], v220 offset:7168
	s_add_u32 s74, s49, s4
	s_addc_u32 s75, s54, s5
	s_add_u32 s74, s74, 0xffffff80
	s_addc_u32 s75, s75, -1
	s_sub_u32 s98, s74, 0x80000
	s_subb_u32 s99, s75, 0
	s_mov_b32 m0, s70
	s_nop 0
	global_load_lds_dwordx4 v1, s[98:99]
	s_nop 1
	s_nop 0
	s_mov_b32 m0, s71
	s_nop 0
	global_load_lds_dwordx4 v217, s[98:99]
	s_nop 1
	s_mov_b32 m0, s46
	s_nop 0
	global_load_lds_dwordx4 v1, s[74:75]
	s_nop 1
	s_nop 0
	s_mov_b32 m0, s47
	s_nop 0
	global_load_lds_dwordx4 v217, s[74:75]
	s_nop 1
	s_waitcnt vmcnt(8)
	s_waitcnt lgkmcnt(0)
	s_barrier
	s_setprio 1
	s_waitcnt lgkmcnt(7)
	v_mfma_f32_16x16x32_bf16 v[2:5], v[132:135], v[164:167], v[2:5]
	v_mfma_f32_16x16x32_bf16 v[62:65], v[140:143], v[164:167], v[62:65]
	s_waitcnt lgkmcnt(5)
	v_mfma_f32_16x16x32_bf16 v[58:61], v[132:135], v[172:175], v[58:61]
	v_mfma_f32_16x16x32_bf16 v[54:57], v[140:143], v[172:175], v[54:57]
	s_waitcnt lgkmcnt(3)
	v_mfma_f32_16x16x32_bf16 v[50:53], v[132:135], v[180:183], v[50:53]
	v_mfma_f32_16x16x32_bf16 v[46:49], v[140:143], v[180:183], v[46:49]
	s_waitcnt lgkmcnt(1)
	v_mfma_f32_16x16x32_bf16 v[42:45], v[132:135], v[188:191], v[42:45]
	v_mfma_f32_16x16x32_bf16 v[38:41], v[140:143], v[188:191], v[38:41]
	v_mfma_f32_16x16x32_bf16 v[34:37], v[148:151], v[164:167], v[34:37]
	v_mfma_f32_16x16x32_bf16 v[30:33], v[156:159], v[164:167], v[30:33]
	v_mfma_f32_16x16x32_bf16 v[26:29], v[148:151], v[172:175], v[26:29]
	v_mfma_f32_16x16x32_bf16 v[22:25], v[156:159], v[172:175], v[22:25]
	v_mfma_f32_16x16x32_bf16 v[18:21], v[148:151], v[180:183], v[18:21]
	v_mfma_f32_16x16x32_bf16 v[14:17], v[156:159], v[180:183], v[14:17]
	v_mfma_f32_16x16x32_bf16 v[10:13], v[148:151], v[188:191], v[10:13]
	v_mfma_f32_16x16x32_bf16 v[6:9], v[156:159], v[188:191], v[6:9]
	v_mfma_f32_16x16x32_bf16 v[2:5], v[136:139], v[168:171], v[2:5]
	v_mfma_f32_16x16x32_bf16 v[62:65], v[144:147], v[168:171], v[62:65]
	v_mfma_f32_16x16x32_bf16 v[58:61], v[136:139], v[176:179], v[58:61]
	v_mfma_f32_16x16x32_bf16 v[54:57], v[144:147], v[176:179], v[54:57]
	v_mfma_f32_16x16x32_bf16 v[50:53], v[136:139], v[184:187], v[50:53]
	v_mfma_f32_16x16x32_bf16 v[46:49], v[144:147], v[184:187], v[46:49]
	s_waitcnt lgkmcnt(0)
	v_mfma_f32_16x16x32_bf16 v[42:45], v[136:139], v[192:195], v[42:45]
	v_mfma_f32_16x16x32_bf16 v[38:41], v[144:147], v[192:195], v[38:41]
	v_mfma_f32_16x16x32_bf16 v[34:37], v[152:155], v[168:171], v[34:37]
	v_mfma_f32_16x16x32_bf16 v[30:33], v[160:163], v[168:171], v[30:33]
	v_mfma_f32_16x16x32_bf16 v[26:29], v[152:155], v[176:179], v[26:29]
	v_mfma_f32_16x16x32_bf16 v[22:25], v[160:163], v[176:179], v[22:25]
	v_mfma_f32_16x16x32_bf16 v[18:21], v[152:155], v[184:187], v[18:21]
	v_mfma_f32_16x16x32_bf16 v[14:17], v[160:163], v[184:187], v[14:17]
	v_mfma_f32_16x16x32_bf16 v[10:13], v[152:155], v[192:195], v[10:13]
	v_mfma_f32_16x16x32_bf16 v[6:9], v[160:163], v[192:195], v[6:9]
	s_setprio 0
	s_barrier
	ds_read_b128 v[164:167], v220 offset:16384
	ds_read_b128 v[168:171], v220 offset:17408
	ds_read_b128 v[172:175], v220 offset:18432
	ds_read_b128 v[176:179], v220 offset:19456
	ds_read_b128 v[180:183], v220 offset:20480
	ds_read_b128 v[184:187], v220 offset:21504
	ds_read_b128 v[188:191], v220 offset:22528
	ds_read_b128 v[192:195], v220 offset:23552
	s_mov_b32 m0, s67
	s_nop 0
	global_load_lds_dwordx4 v216, s[8:9]
	s_nop 1
	s_add_u32 s74, s8, 0x80000
	s_mov_b32 m0, s0
	s_nop 0
	global_load_lds_dwordx4 v218, s[8:9]
	s_nop 1
	s_addc_u32 s75, s9, 0
	s_mov_b32 m0, s1
	s_nop 0
	global_load_lds_dwordx4 v216, s[74:75]
	s_nop 1
	s_nop 0
	s_mov_b32 m0, s35
	s_nop 0
	global_load_lds_dwordx4 v218, s[74:75]
	s_nop 1
	s_nop 0
	s_waitcnt vmcnt(6)
	s_waitcnt lgkmcnt(0)
	s_barrier
; #define PG8_STAGE(bufoff, gbase, voff) do { _Pragma("unroll") for (int _i = 0; _i < 2; ++_i) { \
;         const unsigned m0v_ = (unsigned)(uintptr_t)(lds + (bufoff) + ldsw + _i * 8192); \
;         asm volatile("s_mov_b32 m0, %0\n\ts_nop 0\n\tglobal_load_lds_dwordx4 %1, %2\n\ts_nop 1" :: "s"(m0v_), "v"((voff)[_i]), "s"((const char*)(gbase)) : "m0", "memory"); } } while (0)
; #define PG8_LDA(dst, b, h) do { _Pragma("unroll") for (int m = 0; m < 4; ++m) _Pragma("unroll") for (int k = 0; k < 2; ++k) dst[m][k] = *(const LAS bf16x8*)(lds + PG8_SA(b, h) + aoff + m * 2048 + k * 1024); } while (0)
; #define PG8_LDB(dst, b, h) do { _Pragma("unroll") for (int n = 0; n < 2; ++n) _Pragma("unroll") for (int k = 0; k < 2; ++k) dst[n][k] = *(const LAS bf16x8*)(lds + PG8_SB(b, h) + boff + n * 2048 + k * 1024); } while (0)
; #define PG8_MMA(ai, bj, At, Bt) do { _Pragma("unroll") for (int m = 0; m < 4; ++m) _Pragma("unroll") for (int n = 0; n < 2; ++n) _Pragma("unroll") for (int k = 0; k < 2; ++k) \
;         acc[ai][bj][m][n] = __builtin_amdgcn_mfma_f32_16x16x32_bf16(Bt[n][k], At[m][k], acc[ai][bj][m][n], 0, 0, 0); } while (0)
; #define PG8_WAIT_V(n) asm volatile("s_waitcnt vmcnt(" #n ")" ::: "memory")
; #define PG8_WAIT_L(n) asm volatile("s_waitcnt lgkmcnt(" #n ")" ::: "memory")
; #define PG8_BAR __builtin_amdgcn_s_barrier()
; #define PG8_SCHED __builtin_amdgcn_sched_barrier(0)
; template <class Prob, class Epi, class Sched>
; __device__ __forceinline__ void gemm_phase(LAS unsigned char* lds, const Prob& P, const Sched& S, const Epi& E) {
;     ...
;             PG8_WAIT_V(8); PG8_WAIT_L(0); PG8_BAR; __builtin_amdgcn_s_setprio(1); PG8_MMA(1, 0, At, B0); PG8_MMA(1, 1, At, B1); __builtin_amdgcn_s_setprio(0); PG8_BAR; PG8_SCHED;
;             PG8_LDB(B0, 1, 0); PG8_LDB(B1, 1, 1); PG8_SCHED; PG8_LDA(At, 1, 0); PG8_STAGE(PG8_SA(0, 1), a2 + hstepA, voffA);
;             PG8_WAIT_V(8); PG8_WAIT_L(0); PG8_BAR; __builtin_amdgcn_s_setprio(1); PG8_MMA(0, 0, At, B0); PG8_MMA(0, 1, At, B1); __builtin_amdgcn_s_setprio(0); PG8_BAR; PG8_SCHED;
	s_setprio 1
	s_waitcnt lgkmcnt(7)
	v_mfma_f32_16x16x32_bf16 v[126:129], v[132:135], v[164:167], v[126:129]
	v_mfma_f32_16x16x32_bf16 v[122:125], v[140:143], v[164:167], v[122:125]
	s_waitcnt lgkmcnt(5)
	v_mfma_f32_16x16x32_bf16 v[118:121], v[132:135], v[172:175], v[118:121]
	v_mfma_f32_16x16x32_bf16 v[114:117], v[140:143], v[172:175], v[114:117]
	s_waitcnt lgkmcnt(3)
	v_mfma_f32_16x16x32_bf16 v[110:113], v[132:135], v[180:183], v[110:113]
	v_mfma_f32_16x16x32_bf16 v[106:109], v[140:143], v[180:183], v[106:109]
	s_waitcnt lgkmcnt(1)
	v_mfma_f32_16x16x32_bf16 v[102:105], v[132:135], v[188:191], v[102:105]
	v_mfma_f32_16x16x32_bf16 v[98:101], v[140:143], v[188:191], v[98:101]
	v_mfma_f32_16x16x32_bf16 v[94:97], v[148:151], v[164:167], v[94:97]
	v_mfma_f32_16x16x32_bf16 v[90:93], v[156:159], v[164:167], v[90:93]
	v_mfma_f32_16x16x32_bf16 v[86:89], v[148:151], v[172:175], v[86:89]
	v_mfma_f32_16x16x32_bf16 v[82:85], v[156:159], v[172:175], v[82:85]
	v_mfma_f32_16x16x32_bf16 v[78:81], v[148:151], v[180:183], v[78:81]
	v_mfma_f32_16x16x32_bf16 v[74:77], v[156:159], v[180:183], v[74:77]
	v_mfma_f32_16x16x32_bf16 v[70:73], v[148:151], v[188:191], v[70:73]
	v_mfma_f32_16x16x32_bf16 v[66:69], v[156:159], v[188:191], v[66:69]
	v_mfma_f32_16x16x32_bf16 v[126:129], v[136:139], v[168:171], v[126:129]
	v_mfma_f32_16x16x32_bf16 v[122:125], v[144:147], v[168:171], v[122:125]
	v_mfma_f32_16x16x32_bf16 v[118:121], v[136:139], v[176:179], v[118:121]
	v_mfma_f32_16x16x32_bf16 v[114:117], v[144:147], v[176:179], v[114:117]
	v_mfma_f32_16x16x32_bf16 v[110:113], v[136:139], v[184:187], v[110:113]
	v_mfma_f32_16x16x32_bf16 v[106:109], v[144:147], v[184:187], v[106:109]
	s_waitcnt lgkmcnt(0)
	v_mfma_f32_16x16x32_bf16 v[102:105], v[136:139], v[192:195], v[102:105]
	v_mfma_f32_16x16x32_bf16 v[98:101], v[144:147], v[192:195], v[98:101]
	v_mfma_f32_16x16x32_bf16 v[94:97], v[152:155], v[168:171], v[94:97]
	v_mfma_f32_16x16x32_bf16 v[90:93], v[160:163], v[168:171], v[90:93]
	v_mfma_f32_16x16x32_bf16 v[86:89], v[152:155], v[176:179], v[86:89]
	v_mfma_f32_16x16x32_bf16 v[82:85], v[160:163], v[176:179], v[82:85]
	v_mfma_f32_16x16x32_bf16 v[78:81], v[152:155], v[184:187], v[78:81]
	v_mfma_f32_16x16x32_bf16 v[74:77], v[160:163], v[184:187], v[74:77]
	v_mfma_f32_16x16x32_bf16 v[70:73], v[152:155], v[192:195], v[70:73]
	v_mfma_f32_16x16x32_bf16 v[66:69], v[160:163], v[192:195], v[66:69]
	s_setprio 0
	s_barrier
	v_add_u32_e32 v130, 0x18000, v219
	ds_read_b128 v[132:135], v130
	ds_read_b128 v[136:139], v130 offset:1024
	ds_read_b128 v[140:143], v130 offset:2048
	ds_read_b128 v[144:147], v130 offset:3072
	v_add_u32_e32 v130, 0x1c000, v219
	ds_read_b128 v[148:151], v130
	ds_read_b128 v[152:155], v130 offset:1024
	ds_read_b128 v[156:159], v130 offset:2048
	ds_read_b128 v[160:163], v130 offset:3072
	ds_read_b128 v[164:167], v220 offset:32768
	ds_read_b128 v[168:171], v220 offset:33792
	ds_read_b128 v[172:175], v220 offset:34816
	ds_read_b128 v[176:179], v220 offset:35840
	ds_read_b128 v[180:183], v220 offset:36864
	ds_read_b128 v[184:187], v220 offset:37888
	ds_read_b128 v[188:191], v220 offset:38912
	ds_read_b128 v[192:195], v220 offset:39936
	s_mov_b32 m0, s41
	s_nop 0
	global_load_lds_dwordx4 v1, s[10:11]
	s_nop 1
	s_nop 0
	s_mov_b32 m0, s3
	s_nop 0
	global_load_lds_dwordx4 v217, s[10:11]
	s_nop 1
	s_add_u32 s10, s10, 0x80000
	s_addc_u32 s11, s11, 0
	s_mov_b32 m0, s64
	s_nop 0
	global_load_lds_dwordx4 v1, s[10:11]
	s_nop 1
	s_nop 0
	s_mov_b32 m0, s65
	s_nop 0
	global_load_lds_dwordx4 v217, s[10:11]
	s_nop 1
	s_waitcnt vmcnt(8)
	s_waitcnt lgkmcnt(0)
	s_barrier
; #define PG8_STAGE(bufoff, gbase, voff) do { _Pragma("unroll") for (int _i = 0; _i < 2; ++_i) { \
;         const unsigned m0v_ = (unsigned)(uintptr_t)(lds + (bufoff) + ldsw + _i * 8192); \
;         asm volatile("s_mov_b32 m0, %0\n\ts_nop 0\n\tglobal_load_lds_dwordx4 %1, %2\n\ts_nop 1" :: "s"(m0v_), "v"((voff)[_i]), "s"((const char*)(gbase)) : "m0", "memory"); } } while (0)
; #define PG8_LDA(dst, b, h) do { _Pragma("unroll") for (int m = 0; m < 4; ++m) _Pragma("unroll") for (int k = 0; k < 2; ++k) dst[m][k] = *(const LAS bf16x8*)(lds + PG8_SA(b, h) + aoff + m * 2048 + k * 1024); } while (0)
; #define PG8_MMA(ai, bj, At, Bt) do { _Pragma("unroll") for (int m = 0; m < 4; ++m) _Pragma("unroll") for (int n = 0; n < 2; ++n) _Pragma("unroll") for (int k = 0; k < 2; ++k) \
;         acc[ai][bj][m][n] = __builtin_amdgcn_mfma_f32_16x16x32_bf16(Bt[n][k], At[m][k], acc[ai][bj][m][n], 0, 0, 0); } while (0)
; #define PG8_WAIT_V(n) asm volatile("s_waitcnt vmcnt(" #n ")" ::: "memory")
; #define PG8_WAIT_L(n) asm volatile("s_waitcnt lgkmcnt(" #n ")" ::: "memory")
; #define PG8_BAR __builtin_amdgcn_s_barrier()
; #define PG8_SCHED __builtin_amdgcn_sched_barrier(0)
; template <class Prob, class Epi, class Sched>
; __device__ __forceinline__ void gemm_phase(LAS unsigned char* lds, const Prob& P, const Sched& S, const Epi& E) {
;     ...
;             PG8_WAIT_V(8); PG8_WAIT_L(0); PG8_BAR; __builtin_amdgcn_s_setprio(1); PG8_MMA(0, 0, At, B0); PG8_MMA(0, 1, At, B1); __builtin_amdgcn_s_setprio(0); PG8_BAR; PG8_SCHED;
;             PG8_LDA(At, 1, 1); PG8_STAGE(PG8_SB(1, 0), b3, voffB); PG8_STAGE(PG8_SB(1, 1), b3 + hstepB, voffB); PG8_STAGE(PG8_SA(1, 0), a3, voffA);
;             PG8_WAIT_V(8); PG8_WAIT_L(0); PG8_BAR; __builtin_amdgcn_s_setprio(1); PG8_MMA(1, 0, At, B0); PG8_MMA(1, 1, At, B1); __builtin_amdgcn_s_setprio(0); PG8_BAR; PG8_SCHED;
;         }
;         if (wr == 0) PG8_BAR;
	s_setprio 1
	s_waitcnt lgkmcnt(7)
	v_mfma_f32_16x16x32_bf16 v[2:5], v[132:135], v[164:167], v[2:5]
	v_mfma_f32_16x16x32_bf16 v[62:65], v[140:143], v[164:167], v[62:65]
	s_waitcnt lgkmcnt(5)
	v_mfma_f32_16x16x32_bf16 v[58:61], v[132:135], v[172:175], v[58:61]
	v_mfma_f32_16x16x32_bf16 v[54:57], v[140:143], v[172:175], v[54:57]
	s_waitcnt lgkmcnt(3)
	v_mfma_f32_16x16x32_bf16 v[50:53], v[132:135], v[180:183], v[50:53]
	v_mfma_f32_16x16x32_bf16 v[46:49], v[140:143], v[180:183], v[46:49]
	s_waitcnt lgkmcnt(1)
	v_mfma_f32_16x16x32_bf16 v[42:45], v[132:135], v[188:191], v[42:45]
	v_mfma_f32_16x16x32_bf16 v[38:41], v[140:143], v[188:191], v[38:41]
	v_mfma_f32_16x16x32_bf16 v[34:37], v[148:151], v[164:167], v[34:37]
	v_mfma_f32_16x16x32_bf16 v[30:33], v[156:159], v[164:167], v[30:33]
	v_mfma_f32_16x16x32_bf16 v[26:29], v[148:151], v[172:175], v[26:29]
	v_mfma_f32_16x16x32_bf16 v[22:25], v[156:159], v[172:175], v[22:25]
	v_mfma_f32_16x16x32_bf16 v[18:21], v[148:151], v[180:183], v[18:21]
	v_mfma_f32_16x16x32_bf16 v[14:17], v[156:159], v[180:183], v[14:17]
	v_mfma_f32_16x16x32_bf16 v[10:13], v[148:151], v[188:191], v[10:13]
	v_mfma_f32_16x16x32_bf16 v[6:9], v[156:159], v[188:191], v[6:9]
	v_mfma_f32_16x16x32_bf16 v[2:5], v[136:139], v[168:171], v[2:5]
	v_mfma_f32_16x16x32_bf16 v[62:65], v[144:147], v[168:171], v[62:65]
	v_mfma_f32_16x16x32_bf16 v[58:61], v[136:139], v[176:179], v[58:61]
	v_mfma_f32_16x16x32_bf16 v[54:57], v[144:147], v[176:179], v[54:57]
	v_mfma_f32_16x16x32_bf16 v[50:53], v[136:139], v[184:187], v[50:53]
	v_mfma_f32_16x16x32_bf16 v[46:49], v[144:147], v[184:187], v[46:49]
	s_waitcnt lgkmcnt(0)
	v_mfma_f32_16x16x32_bf16 v[42:45], v[136:139], v[192:195], v[42:45]
	v_mfma_f32_16x16x32_bf16 v[38:41], v[144:147], v[192:195], v[38:41]
	v_mfma_f32_16x16x32_bf16 v[34:37], v[152:155], v[168:171], v[34:37]
	v_mfma_f32_16x16x32_bf16 v[30:33], v[160:163], v[168:171], v[30:33]
	v_mfma_f32_16x16x32_bf16 v[26:29], v[152:155], v[176:179], v[26:29]
	v_mfma_f32_16x16x32_bf16 v[22:25], v[160:163], v[176:179], v[22:25]
	v_mfma_f32_16x16x32_bf16 v[18:21], v[152:155], v[184:187], v[18:21]
	v_mfma_f32_16x16x32_bf16 v[14:17], v[160:163], v[184:187], v[14:17]
	v_mfma_f32_16x16x32_bf16 v[10:13], v[152:155], v[192:195], v[10:13]
	v_mfma_f32_16x16x32_bf16 v[6:9], v[160:163], v[192:195], v[6:9]
	s_setprio 0
	s_barrier
	ds_read_b128 v[164:167], v220 offset:49152
	ds_read_b128 v[168:171], v220 offset:50176
	ds_read_b128 v[172:175], v220 offset:51200
	ds_read_b128 v[176:179], v220 offset:52224
	ds_read_b128 v[180:183], v220 offset:53248
	ds_read_b128 v[184:187], v220 offset:54272
	ds_read_b128 v[188:191], v220 offset:55296
	ds_read_b128 v[192:195], v220 offset:56320
	s_add_u32 s10, s8, 0x80
	s_addc_u32 s11, s9, 0
	s_mov_b32 m0, s62
	s_nop 0
	global_load_lds_dwordx4 v216, s[10:11]
	s_nop 1
	s_add_u32 s8, s8, 0x80080
	s_mov_b32 m0, s63
	s_nop 0
	global_load_lds_dwordx4 v218, s[10:11]
	s_nop 1
	s_addc_u32 s9, s9, 0
	s_mov_b32 m0, s44
	s_nop 0
	global_load_lds_dwordx4 v216, s[8:9]
	s_nop 1
	s_nop 0
	s_mov_b32 m0, s45
	s_nop 0
	global_load_lds_dwordx4 v218, s[8:9]
	s_nop 1
	s_nop 0
	s_waitcnt vmcnt(6)
	s_waitcnt lgkmcnt(0)
	s_barrier
	s_setprio 1
	s_waitcnt lgkmcnt(7)
	v_mfma_f32_16x16x32_bf16 v[126:129], v[132:135], v[164:167], v[126:129]
	v_mfma_f32_16x16x32_bf16 v[122:125], v[140:143], v[164:167], v[122:125]
	s_waitcnt lgkmcnt(5)
	v_mfma_f32_16x16x32_bf16 v[118:121], v[132:135], v[172:175], v[118:121]
	v_mfma_f32_16x16x32_bf16 v[114:117], v[140:143], v[172:175], v[114:117]
	s_waitcnt lgkmcnt(3)
	v_mfma_f32_16x16x32_bf16 v[110:113], v[132:135], v[180:183], v[110:113]
	v_mfma_f32_16x16x32_bf16 v[106:109], v[140:143], v[180:183], v[106:109]
	s_waitcnt lgkmcnt(1)
	v_mfma_f32_16x16x32_bf16 v[102:105], v[132:135], v[188:191], v[102:105]
	v_mfma_f32_16x16x32_bf16 v[98:101], v[140:143], v[188:191], v[98:101]
	v_mfma_f32_16x16x32_bf16 v[94:97], v[148:151], v[164:167], v[94:97]
	v_mfma_f32_16x16x32_bf16 v[90:93], v[156:159], v[164:167], v[90:93]
	v_mfma_f32_16x16x32_bf16 v[86:89], v[148:151], v[172:175], v[86:89]
	v_mfma_f32_16x16x32_bf16 v[82:85], v[156:159], v[172:175], v[82:85]
	v_mfma_f32_16x16x32_bf16 v[78:81], v[148:151], v[180:183], v[78:81]
	v_mfma_f32_16x16x32_bf16 v[74:77], v[156:159], v[180:183], v[74:77]
	v_mfma_f32_16x16x32_bf16 v[70:73], v[148:151], v[188:191], v[70:73]
	v_mfma_f32_16x16x32_bf16 v[66:69], v[156:159], v[188:191], v[66:69]
	v_mfma_f32_16x16x32_bf16 v[126:129], v[136:139], v[168:171], v[126:129]
	v_mfma_f32_16x16x32_bf16 v[122:125], v[144:147], v[168:171], v[122:125]
	v_mfma_f32_16x16x32_bf16 v[118:121], v[136:139], v[176:179], v[118:121]
	v_mfma_f32_16x16x32_bf16 v[114:117], v[144:147], v[176:179], v[114:117]
	v_mfma_f32_16x16x32_bf16 v[110:113], v[136:139], v[184:187], v[110:113]
	v_mfma_f32_16x16x32_bf16 v[106:109], v[144:147], v[184:187], v[106:109]
	s_waitcnt lgkmcnt(0)
	v_mfma_f32_16x16x32_bf16 v[102:105], v[136:139], v[192:195], v[102:105]
	v_mfma_f32_16x16x32_bf16 v[98:101], v[144:147], v[192:195], v[98:101]
	v_mfma_f32_16x16x32_bf16 v[94:97], v[152:155], v[168:171], v[94:97]
	v_mfma_f32_16x16x32_bf16 v[90:93], v[160:163], v[168:171], v[90:93]
	v_mfma_f32_16x16x32_bf16 v[86:89], v[152:155], v[176:179], v[86:89]
	v_mfma_f32_16x16x32_bf16 v[82:85], v[160:163], v[176:179], v[82:85]
	v_mfma_f32_16x16x32_bf16 v[78:81], v[152:155], v[184:187], v[78:81]
	v_mfma_f32_16x16x32_bf16 v[74:77], v[160:163], v[184:187], v[74:77]
	v_mfma_f32_16x16x32_bf16 v[70:73], v[152:155], v[192:195], v[70:73]
	v_mfma_f32_16x16x32_bf16 v[66:69], v[160:163], v[192:195], v[66:69]
	s_setprio 0
	s_barrier
	s_add_u32 s4, s4, 0x100
	s_addc_u32 s5, s5, 0
	s_cmp_ge_i32 s68, s53
	s_mov_b32 s6, s68
	s_cbranch_scc0 .LBB0_451
	v_readlane_b32 s4, v247, 39
	v_readlane_b32 s5, v247, 40
	s_and_b64 vcc, exec, s[4:5]
	s_cbranch_vccz .LBB0_454
	s_barrier

; #define PG8_STAGE(bufoff, gbase, voff) do { _Pragma("unroll") for (int _i = 0; _i < 2; ++_i) { \
;         const unsigned m0v_ = (unsigned)(uintptr_t)(lds + (bufoff) + ldsw + _i * 8192); \
;         asm volatile("s_mov_b32 m0, %0\n\ts_nop 0\n\tglobal_load_lds_dwordx4 %1, %2\n\ts_nop 1" :: "s"(m0v_), "v"((voff)[_i]), "s"((const char*)(gbase)) : "m0", "memory"); } } while (0)
; #define PG8_LDA(dst, b, h) do { _Pragma("unroll") for (int m = 0; m < 4; ++m) _Pragma("unroll") for (int k = 0; k < 2; ++k) dst[m][k] = *(const LAS bf16x8*)(lds + PG8_SA(b, h) + aoff + m * 2048 + k * 1024); } while (0)
; #define PG8_LDB(dst, b, h) do { _Pragma("unroll") for (int n = 0; n < 2; ++n) _Pragma("unroll") for (int k = 0; k < 2; ++k) dst[n][k] = *(const LAS bf16x8*)(lds + PG8_SB(b, h) + boff + n * 2048 + k * 1024); } while (0)
; #define PG8_MMA(ai, bj, At, Bt) do { _Pragma("unroll") for (int m = 0; m < 4; ++m) _Pragma("unroll") for (int n = 0; n < 2; ++n) _Pragma("unroll") for (int k = 0; k < 2; ++k) \
;         acc[ai][bj][m][n] = __builtin_amdgcn_mfma_f32_16x16x32_bf16(Bt[n][k], At[m][k], acc[ai][bj][m][n], 0, 0, 0); } while (0)
; #define PG8_WAIT_V(n) asm volatile("s_waitcnt vmcnt(" #n ")" ::: "memory")
; #define PG8_WAIT_L(n) asm volatile("s_waitcnt lgkmcnt(" #n ")" ::: "memory")
; template <class Prob, class Epi, class Sched>
; __device__ __forceinline__ void gemm_phase(LAS unsigned char* lds, const Prob& P, const Sched& S, const Epi& E) {
;     ...
;             const char* a1 = cA + (size_t)(t + 1) * kstep;
;             const char* a2 = last ? nA : cA + (size_t)(t + 2) * kstep; const char* b2 = last ? nB : cB + (size_t)(t + 2) * kstep;
;             const char* a3 = a2 + kstep; const char* b3 = b2 + kstep;
;             PG8_LDB(B0, 0, 0); PG8_LDB(B1, 0, 1); PG8_SCHED; PG8_LDA(At, 0, 0); PG8_STAGE(PG8_SA(1, 1), a1 + hstepA, voffA);
;             PG8_WAIT_V(8); PG8_WAIT_L(0); PG8_BAR; __builtin_amdgcn_s_setprio(1); PG8_MMA(0, 0, At, B0); PG8_MMA(0, 1, At, B1); __builtin_amdgcn_s_setprio(0); PG8_BAR; PG8_SCHED;
;             PG8_LDA(At, 0, 1); PG8_STAGE(PG8_SB(0, 0), b2, voffB); PG8_STAGE(PG8_SB(0, 1), b2 + hstepB, voffB); PG8_STAGE(PG8_SA(0, 0), a2, voffA);
;             PG8_WAIT_V(8); PG8_WAIT_L(0); PG8_BAR; __builtin_amdgcn_s_setprio(1); PG8_MMA(1, 0, At, B0); PG8_MMA(1, 1, At, B1); __builtin_amdgcn_s_setprio(0); PG8_BAR; PG8_SCHED;
.LBB0_866:
	v_add_u32_e32 v130, 0x10000, v143
	ds_read_b128 v[136:139], v130
	ds_read_b128 v[148:151], v130 offset:1024
	ds_read_b128 v[152:155], v130 offset:2048
	ds_read_b128 v[156:159], v130 offset:3072
	v_add_u32_e32 v130, 0x14000, v143
	ds_read_b128 v[160:163], v130
	ds_read_b128 v[164:167], v130 offset:1024
	ds_read_b128 v[168:171], v130 offset:2048
	ds_read_b128 v[172:175], v130 offset:3072
	s_cmp_eq_u32 s83, 28
	s_cselect_b32 s64, s48, s47
	s_cselect_b32 s65, s49, s80
	s_cselect_b32 s62, s50, s81
	s_cselect_b32 s63, s51, s82
	s_add_u32 s54, s64, 0x80
	s_addc_u32 s55, s65, 0
	ds_read_b128 v[176:179], v144
	ds_read_b128 v[180:183], v144 offset:1024
	ds_read_b128 v[184:187], v144 offset:2048
	ds_read_b128 v[188:191], v144 offset:3072
	ds_read_b128 v[192:195], v144 offset:4096
	ds_read_b128 v[196:199], v144 offset:5120
	ds_read_b128 v[200:203], v144 offset:6144
	ds_read_b128 v[204:207], v144 offset:7168
	s_sub_u32 s98, s4, 0x80000
	s_subb_u32 s99, s5, 0
	s_mov_b32 m0, s69
	s_nop 0
	global_load_lds_dwordx4 v1, s[98:99]
	s_nop 1
	s_nop 0
	s_mov_b32 m0, s70
	s_nop 0
	global_load_lds_dwordx4 v141, s[98:99]
	s_nop 1
	s_mov_b32 m0, s74
	s_nop 0
	global_load_lds_dwordx4 v1, s[4:5]
	s_nop 1
	s_nop 0
	s_mov_b32 m0, s75
	s_nop 0
	global_load_lds_dwordx4 v141, s[4:5]
	s_nop 1
	s_waitcnt vmcnt(8)
	s_waitcnt lgkmcnt(0)
	s_barrier
	s_setprio 1
	s_waitcnt lgkmcnt(7)
	v_mfma_f32_16x16x32_bf16 v[2:5], v[136:139], v[176:179], v[2:5]
	v_mfma_f32_16x16x32_bf16 v[22:25], v[152:155], v[176:179], v[22:25]
	s_waitcnt lgkmcnt(5)
	v_mfma_f32_16x16x32_bf16 v[6:9], v[136:139], v[184:187], v[6:9]
	v_mfma_f32_16x16x32_bf16 v[26:29], v[152:155], v[184:187], v[26:29]
	s_waitcnt lgkmcnt(3)
	v_mfma_f32_16x16x32_bf16 v[14:17], v[136:139], v[192:195], v[14:17]
	v_mfma_f32_16x16x32_bf16 v[42:45], v[152:155], v[192:195], v[42:45]
	s_waitcnt lgkmcnt(1)
	v_mfma_f32_16x16x32_bf16 v[34:37], v[136:139], v[200:203], v[34:37]
	v_mfma_f32_16x16x32_bf16 v[54:57], v[152:155], v[200:203], v[54:57]
	v_mfma_f32_16x16x32_bf16 v[10:13], v[160:163], v[176:179], v[10:13]
	v_mfma_f32_16x16x32_bf16 v[30:33], v[168:171], v[176:179], v[30:33]
	v_mfma_f32_16x16x32_bf16 v[18:21], v[160:163], v[184:187], v[18:21]
	v_mfma_f32_16x16x32_bf16 v[46:49], v[168:171], v[184:187], v[46:49]
	v_mfma_f32_16x16x32_bf16 v[38:41], v[160:163], v[192:195], v[38:41]
	v_mfma_f32_16x16x32_bf16 v[58:61], v[168:171], v[192:195], v[58:61]
	v_mfma_f32_16x16x32_bf16 v[50:53], v[160:163], v[200:203], v[50:53]
	v_mfma_f32_16x16x32_bf16 v[66:69], v[168:171], v[200:203], v[66:69]
	v_mfma_f32_16x16x32_bf16 v[2:5], v[148:151], v[180:183], v[2:5]
	v_mfma_f32_16x16x32_bf16 v[22:25], v[156:159], v[180:183], v[22:25]
	v_mfma_f32_16x16x32_bf16 v[6:9], v[148:151], v[188:191], v[6:9]
	v_mfma_f32_16x16x32_bf16 v[26:29], v[156:159], v[188:191], v[26:29]
	v_mfma_f32_16x16x32_bf16 v[14:17], v[148:151], v[196:199], v[14:17]
	v_mfma_f32_16x16x32_bf16 v[42:45], v[156:159], v[196:199], v[42:45]
	s_waitcnt lgkmcnt(0)
	v_mfma_f32_16x16x32_bf16 v[34:37], v[148:151], v[204:207], v[34:37]
	v_mfma_f32_16x16x32_bf16 v[54:57], v[156:159], v[204:207], v[54:57]
	v_mfma_f32_16x16x32_bf16 v[10:13], v[164:167], v[180:183], v[10:13]
	v_mfma_f32_16x16x32_bf16 v[30:33], v[172:175], v[180:183], v[30:33]
	v_mfma_f32_16x16x32_bf16 v[18:21], v[164:167], v[188:191], v[18:21]
	v_mfma_f32_16x16x32_bf16 v[46:49], v[172:175], v[188:191], v[46:49]
	v_mfma_f32_16x16x32_bf16 v[38:41], v[164:167], v[196:199], v[38:41]
	v_mfma_f32_16x16x32_bf16 v[58:61], v[172:175], v[196:199], v[58:61]
	v_mfma_f32_16x16x32_bf16 v[50:53], v[164:167], v[204:207], v[50:53]
	v_mfma_f32_16x16x32_bf16 v[66:69], v[172:175], v[204:207], v[66:69]
	s_setprio 0
	s_barrier
	ds_read_b128 v[176:179], v144 offset:16384
	ds_read_b128 v[180:183], v144 offset:17408
	ds_read_b128 v[184:187], v144 offset:18432
	ds_read_b128 v[188:191], v144 offset:19456
	ds_read_b128 v[192:195], v144 offset:20480
	ds_read_b128 v[196:199], v144 offset:21504
	ds_read_b128 v[200:203], v144 offset:22528
	ds_read_b128 v[204:207], v144 offset:23552
	s_mov_b32 m0, s41
	s_nop 0
	global_load_lds_dwordx4 v140, s[62:63]
	s_nop 1
	s_add_u32 s84, s62, 0x80000
	s_mov_b32 m0, s53
	s_nop 0
	global_load_lds_dwordx4 v142, s[62:63]
	s_nop 1
	s_addc_u32 s85, s63, 0
	s_mov_b32 m0, s56
	s_nop 0
	global_load_lds_dwordx4 v140, s[84:85]
	s_nop 1
	s_nop 0
	s_mov_b32 m0, s57
	s_nop 0
	global_load_lds_dwordx4 v142, s[84:85]
	s_nop 1
	s_nop 0
	s_waitcnt vmcnt(6)
	s_waitcnt lgkmcnt(0)
	s_barrier
; #define PG8_STAGE(bufoff, gbase, voff) do { _Pragma("unroll") for (int _i = 0; _i < 2; ++_i) { \
;         const unsigned m0v_ = (unsigned)(uintptr_t)(lds + (bufoff) + ldsw + _i * 8192); \
;         asm volatile("s_mov_b32 m0, %0\n\ts_nop 0\n\tglobal_load_lds_dwordx4 %1, %2\n\ts_nop 1" :: "s"(m0v_), "v"((voff)[_i]), "s"((const char*)(gbase)) : "m0", "memory"); } } while (0)
; #define PG8_LDA(dst, b, h) do { _Pragma("unroll") for (int m = 0; m < 4; ++m) _Pragma("unroll") for (int k = 0; k < 2; ++k) dst[m][k] = *(const LAS bf16x8*)(lds + PG8_SA(b, h) + aoff + m * 2048 + k * 1024); } while (0)
; #define PG8_LDB(dst, b, h) do { _Pragma("unroll") for (int n = 0; n < 2; ++n) _Pragma("unroll") for (int k = 0; k < 2; ++k) dst[n][k] = *(const LAS bf16x8*)(lds + PG8_SB(b, h) + boff + n * 2048 + k * 1024); } while (0)
; #define PG8_MMA(ai, bj, At, Bt) do { _Pragma("unroll") for (int m = 0; m < 4; ++m) _Pragma("unroll") for (int n = 0; n < 2; ++n) _Pragma("unroll") for (int k = 0; k < 2; ++k) \
;         acc[ai][bj][m][n] = __builtin_amdgcn_mfma_f32_16x16x32_bf16(Bt[n][k], At[m][k], acc[ai][bj][m][n], 0, 0, 0); } while (0)
; #define PG8_WAIT_V(n) asm volatile("s_waitcnt vmcnt(" #n ")" ::: "memory")
; #define PG8_WAIT_L(n) asm volatile("s_waitcnt lgkmcnt(" #n ")" ::: "memory")
; #define PG8_BAR __builtin_amdgcn_s_barrier()
; #define PG8_SCHED __builtin_amdgcn_sched_barrier(0)
; template <class Prob, class Epi, class Sched>
; __device__ __forceinline__ void gemm_phase(LAS unsigned char* lds, const Prob& P, const Sched& S, const Epi& E) {
;     ...
;             PG8_WAIT_V(8); PG8_WAIT_L(0); PG8_BAR; __builtin_amdgcn_s_setprio(1); PG8_MMA(1, 0, At, B0); PG8_MMA(1, 1, At, B1); __builtin_amdgcn_s_setprio(0); PG8_BAR; PG8_SCHED;
;             PG8_LDB(B0, 1, 0); PG8_LDB(B1, 1, 1); PG8_SCHED; PG8_LDA(At, 1, 0); PG8_STAGE(PG8_SA(0, 1), a2 + hstepA, voffA);
;             PG8_WAIT_V(8); PG8_WAIT_L(0); PG8_BAR; __builtin_amdgcn_s_setprio(1); PG8_MMA(0, 0, At, B0); PG8_MMA(0, 1, At, B1); __builtin_amdgcn_s_setprio(0); PG8_BAR; PG8_SCHED;
	s_setprio 1
	s_waitcnt lgkmcnt(7)
	v_mfma_f32_16x16x32_bf16 v[62:65], v[136:139], v[176:179], v[62:65]
	v_mfma_f32_16x16x32_bf16 v[78:81], v[152:155], v[176:179], v[78:81]
	s_waitcnt lgkmcnt(5)
	v_mfma_f32_16x16x32_bf16 v[70:73], v[136:139], v[184:187], v[70:73]
	v_mfma_f32_16x16x32_bf16 v[90:93], v[152:155], v[184:187], v[90:93]
	s_waitcnt lgkmcnt(3)
	v_mfma_f32_16x16x32_bf16 v[82:85], v[136:139], v[192:195], v[82:85]
	v_mfma_f32_16x16x32_bf16 v[106:109], v[152:155], v[192:195], v[106:109]
	s_waitcnt lgkmcnt(1)
	v_mfma_f32_16x16x32_bf16 v[98:101], v[136:139], v[200:203], v[98:101]
	v_mfma_f32_16x16x32_bf16 v[118:121], v[152:155], v[200:203], v[118:121]
	v_mfma_f32_16x16x32_bf16 v[74:77], v[160:163], v[176:179], v[74:77]
	v_mfma_f32_16x16x32_bf16 v[94:97], v[168:171], v[176:179], v[94:97]
	v_mfma_f32_16x16x32_bf16 v[86:89], v[160:163], v[184:187], v[86:89]
	v_mfma_f32_16x16x32_bf16 v[110:113], v[168:171], v[184:187], v[110:113]
	v_mfma_f32_16x16x32_bf16 v[102:105], v[160:163], v[192:195], v[102:105]
	v_mfma_f32_16x16x32_bf16 v[122:125], v[168:171], v[192:195], v[122:125]
	v_mfma_f32_16x16x32_bf16 v[114:117], v[160:163], v[200:203], v[114:117]
	v_mfma_f32_16x16x32_bf16 v[126:129], v[168:171], v[200:203], v[126:129]
	v_mfma_f32_16x16x32_bf16 v[62:65], v[148:151], v[180:183], v[62:65]
	v_mfma_f32_16x16x32_bf16 v[78:81], v[156:159], v[180:183], v[78:81]
	v_mfma_f32_16x16x32_bf16 v[70:73], v[148:151], v[188:191], v[70:73]
	v_mfma_f32_16x16x32_bf16 v[90:93], v[156:159], v[188:191], v[90:93]
	v_mfma_f32_16x16x32_bf16 v[82:85], v[148:151], v[196:199], v[82:85]
	v_mfma_f32_16x16x32_bf16 v[106:109], v[156:159], v[196:199], v[106:109]
	s_waitcnt lgkmcnt(0)
	v_mfma_f32_16x16x32_bf16 v[98:101], v[148:151], v[204:207], v[98:101]
	v_mfma_f32_16x16x32_bf16 v[118:121], v[156:159], v[204:207], v[118:121]
	v_mfma_f32_16x16x32_bf16 v[74:77], v[164:167], v[180:183], v[74:77]
	v_mfma_f32_16x16x32_bf16 v[94:97], v[172:175], v[180:183], v[94:97]
	v_mfma_f32_16x16x32_bf16 v[86:89], v[164:167], v[188:191], v[86:89]
	v_mfma_f32_16x16x32_bf16 v[110:113], v[172:175], v[188:191], v[110:113]
	v_mfma_f32_16x16x32_bf16 v[102:105], v[164:167], v[196:199], v[102:105]
	v_mfma_f32_16x16x32_bf16 v[122:125], v[172:175], v[196:199], v[122:125]
	v_mfma_f32_16x16x32_bf16 v[114:117], v[164:167], v[204:207], v[114:117]
	v_mfma_f32_16x16x32_bf16 v[126:129], v[172:175], v[204:207], v[126:129]
	s_setprio 0
	s_barrier
	v_add_u32_e32 v130, 0x18000, v143
	ds_read_b128 v[136:139], v130
	ds_read_b128 v[148:151], v130 offset:1024
	ds_read_b128 v[152:155], v130 offset:2048
	ds_read_b128 v[156:159], v130 offset:3072
	v_add_u32_e32 v130, 0x1c000, v143
	ds_read_b128 v[160:163], v130
	ds_read_b128 v[164:167], v130 offset:1024
	ds_read_b128 v[168:171], v130 offset:2048
	ds_read_b128 v[172:175], v130 offset:3072
	ds_read_b128 v[176:179], v144 offset:32768
	ds_read_b128 v[180:183], v144 offset:33792
	ds_read_b128 v[184:187], v144 offset:34816
	ds_read_b128 v[188:191], v144 offset:35840
	ds_read_b128 v[192:195], v144 offset:36864
	ds_read_b128 v[196:199], v144 offset:37888
	ds_read_b128 v[200:203], v144 offset:38912
	ds_read_b128 v[204:207], v144 offset:39936
	s_mov_b32 m0, s34
	s_nop 0
	global_load_lds_dwordx4 v1, s[64:65]
	s_nop 1
	s_nop 0
	s_mov_b32 m0, s58
	s_nop 0
	global_load_lds_dwordx4 v141, s[64:65]
	s_nop 1
	s_add_u32 s64, s64, 0x80000
	s_addc_u32 s65, s65, 0
	s_mov_b32 m0, s59
	s_nop 0
	global_load_lds_dwordx4 v1, s[64:65]
	s_nop 1
	s_nop 0
	s_mov_b32 m0, s60
	s_nop 0
	global_load_lds_dwordx4 v141, s[64:65]
	s_nop 1
	s_waitcnt vmcnt(8)
	s_waitcnt lgkmcnt(0)
	s_barrier
; #define PG8_STAGE(bufoff, gbase, voff) do { _Pragma("unroll") for (int _i = 0; _i < 2; ++_i) { \
;         const unsigned m0v_ = (unsigned)(uintptr_t)(lds + (bufoff) + ldsw + _i * 8192); \
;         asm volatile("s_mov_b32 m0, %0\n\ts_nop 0\n\tglobal_load_lds_dwordx4 %1, %2\n\ts_nop 1" :: "s"(m0v_), "v"((voff)[_i]), "s"((const char*)(gbase)) : "m0", "memory"); } } while (0)
; #define PG8_LDA(dst, b, h) do { _Pragma("unroll") for (int m = 0; m < 4; ++m) _Pragma("unroll") for (int k = 0; k < 2; ++k) dst[m][k] = *(const LAS bf16x8*)(lds + PG8_SA(b, h) + aoff + m * 2048 + k * 1024); } while (0)
; #define PG8_MMA(ai, bj, At, Bt) do { _Pragma("unroll") for (int m = 0; m < 4; ++m) _Pragma("unroll") for (int n = 0; n < 2; ++n) _Pragma("unroll") for (int k = 0; k < 2; ++k) \
;         acc[ai][bj][m][n] = __builtin_amdgcn_mfma_f32_16x16x32_bf16(Bt[n][k], At[m][k], acc[ai][bj][m][n], 0, 0, 0); } while (0)
; #define PG8_WAIT_V(n) asm volatile("s_waitcnt vmcnt(" #n ")" ::: "memory")
; #define PG8_WAIT_L(n) asm volatile("s_waitcnt lgkmcnt(" #n ")" ::: "memory")
; #define PG8_BAR __builtin_amdgcn_s_barrier()
; #define PG8_SCHED __builtin_amdgcn_sched_barrier(0)
; template <class Prob, class Epi, class Sched>
; __device__ __forceinline__ void gemm_phase(LAS unsigned char* lds, const Prob& P, const Sched& S, const Epi& E) {
;     ...
;             PG8_WAIT_V(8); PG8_WAIT_L(0); PG8_BAR; __builtin_amdgcn_s_setprio(1); PG8_MMA(0, 0, At, B0); PG8_MMA(0, 1, At, B1); __builtin_amdgcn_s_setprio(0); PG8_BAR; PG8_SCHED;
;             PG8_LDA(At, 1, 1); PG8_STAGE(PG8_SB(1, 0), b3, voffB); PG8_STAGE(PG8_SB(1, 1), b3 + hstepB, voffB); PG8_STAGE(PG8_SA(1, 0), a3, voffA);
;             PG8_WAIT_V(8); PG8_WAIT_L(0); PG8_BAR; __builtin_amdgcn_s_setprio(1); PG8_MMA(1, 0, At, B0); PG8_MMA(1, 1, At, B1); __builtin_amdgcn_s_setprio(0); PG8_BAR; PG8_SCHED;
;         }
;         if (wr == 0) PG8_BAR;
	s_setprio 1
	s_waitcnt lgkmcnt(7)
	v_mfma_f32_16x16x32_bf16 v[2:5], v[136:139], v[176:179], v[2:5]
	v_mfma_f32_16x16x32_bf16 v[22:25], v[152:155], v[176:179], v[22:25]
	s_waitcnt lgkmcnt(5)
	v_mfma_f32_16x16x32_bf16 v[6:9], v[136:139], v[184:187], v[6:9]
	v_mfma_f32_16x16x32_bf16 v[26:29], v[152:155], v[184:187], v[26:29]
	s_waitcnt lgkmcnt(3)
	v_mfma_f32_16x16x32_bf16 v[14:17], v[136:139], v[192:195], v[14:17]
	v_mfma_f32_16x16x32_bf16 v[42:45], v[152:155], v[192:195], v[42:45]
	s_waitcnt lgkmcnt(1)
	v_mfma_f32_16x16x32_bf16 v[34:37], v[136:139], v[200:203], v[34:37]
	v_mfma_f32_16x16x32_bf16 v[54:57], v[152:155], v[200:203], v[54:57]
	v_mfma_f32_16x16x32_bf16 v[10:13], v[160:163], v[176:179], v[10:13]
	v_mfma_f32_16x16x32_bf16 v[30:33], v[168:171], v[176:179], v[30:33]
	v_mfma_f32_16x16x32_bf16 v[18:21], v[160:163], v[184:187], v[18:21]
	v_mfma_f32_16x16x32_bf16 v[46:49], v[168:171], v[184:187], v[46:49]
	v_mfma_f32_16x16x32_bf16 v[38:41], v[160:163], v[192:195], v[38:41]
	v_mfma_f32_16x16x32_bf16 v[58:61], v[168:171], v[192:195], v[58:61]
	v_mfma_f32_16x16x32_bf16 v[50:53], v[160:163], v[200:203], v[50:53]
	v_mfma_f32_16x16x32_bf16 v[66:69], v[168:171], v[200:203], v[66:69]
	v_mfma_f32_16x16x32_bf16 v[2:5], v[148:151], v[180:183], v[2:5]
	v_mfma_f32_16x16x32_bf16 v[22:25], v[156:159], v[180:183], v[22:25]
	v_mfma_f32_16x16x32_bf16 v[6:9], v[148:151], v[188:191], v[6:9]
	v_mfma_f32_16x16x32_bf16 v[26:29], v[156:159], v[188:191], v[26:29]
	v_mfma_f32_16x16x32_bf16 v[14:17], v[148:151], v[196:199], v[14:17]
	v_mfma_f32_16x16x32_bf16 v[42:45], v[156:159], v[196:199], v[42:45]
	s_waitcnt lgkmcnt(0)
	v_mfma_f32_16x16x32_bf16 v[34:37], v[148:151], v[204:207], v[34:37]
	v_mfma_f32_16x16x32_bf16 v[54:57], v[156:159], v[204:207], v[54:57]
	v_mfma_f32_16x16x32_bf16 v[10:13], v[164:167], v[180:183], v[10:13]
	v_mfma_f32_16x16x32_bf16 v[30:33], v[172:175], v[180:183], v[30:33]
	v_mfma_f32_16x16x32_bf16 v[18:21], v[164:167], v[188:191], v[18:21]
	v_mfma_f32_16x16x32_bf16 v[46:49], v[172:175], v[188:191], v[46:49]
	v_mfma_f32_16x16x32_bf16 v[38:41], v[164:167], v[196:199], v[38:41]
	v_mfma_f32_16x16x32_bf16 v[58:61], v[172:175], v[196:199], v[58:61]
	v_mfma_f32_16x16x32_bf16 v[50:53], v[164:167], v[204:207], v[50:53]
	v_mfma_f32_16x16x32_bf16 v[66:69], v[172:175], v[204:207], v[66:69]
	s_setprio 0
	s_barrier
	ds_read_b128 v[176:179], v144 offset:49152
	ds_read_b128 v[180:183], v144 offset:50176
	ds_read_b128 v[184:187], v144 offset:51200
	ds_read_b128 v[188:191], v144 offset:52224
	ds_read_b128 v[192:195], v144 offset:53248
	ds_read_b128 v[196:199], v144 offset:54272
	ds_read_b128 v[200:203], v144 offset:55296
	ds_read_b128 v[204:207], v144 offset:56320
	s_add_u32 s64, s62, 0x80
	s_addc_u32 s65, s63, 0
	s_mov_b32 m0, s67
	s_nop 0
	global_load_lds_dwordx4 v140, s[64:65]
	s_nop 1
	s_add_u32 s62, s62, 0x80080
	s_mov_b32 m0, s68
	s_nop 0
	global_load_lds_dwordx4 v142, s[64:65]
	s_nop 1
	s_addc_u32 s63, s63, 0
	s_mov_b32 m0, s71
	s_nop 0
	global_load_lds_dwordx4 v140, s[62:63]
	s_nop 1
	s_nop 0
	s_mov_b32 m0, s72
	s_nop 0
	global_load_lds_dwordx4 v142, s[62:63]
	s_nop 1
	s_nop 0
	s_waitcnt vmcnt(6)
	s_waitcnt lgkmcnt(0)
	s_barrier
	s_setprio 1
	s_waitcnt lgkmcnt(7)
	v_mfma_f32_16x16x32_bf16 v[62:65], v[136:139], v[176:179], v[62:65]
	v_mfma_f32_16x16x32_bf16 v[78:81], v[152:155], v[176:179], v[78:81]
	s_waitcnt lgkmcnt(5)
	v_mfma_f32_16x16x32_bf16 v[70:73], v[136:139], v[184:187], v[70:73]
	v_mfma_f32_16x16x32_bf16 v[90:93], v[152:155], v[184:187], v[90:93]
	s_waitcnt lgkmcnt(3)
	v_mfma_f32_16x16x32_bf16 v[82:85], v[136:139], v[192:195], v[82:85]
	v_mfma_f32_16x16x32_bf16 v[106:109], v[152:155], v[192:195], v[106:109]
	s_waitcnt lgkmcnt(1)
	v_mfma_f32_16x16x32_bf16 v[98:101], v[136:139], v[200:203], v[98:101]
	v_mfma_f32_16x16x32_bf16 v[118:121], v[152:155], v[200:203], v[118:121]
	v_mfma_f32_16x16x32_bf16 v[74:77], v[160:163], v[176:179], v[74:77]
	v_mfma_f32_16x16x32_bf16 v[94:97], v[168:171], v[176:179], v[94:97]
	v_mfma_f32_16x16x32_bf16 v[86:89], v[160:163], v[184:187], v[86:89]
	v_mfma_f32_16x16x32_bf16 v[110:113], v[168:171], v[184:187], v[110:113]
	v_mfma_f32_16x16x32_bf16 v[102:105], v[160:163], v[192:195], v[102:105]
	v_mfma_f32_16x16x32_bf16 v[122:125], v[168:171], v[192:195], v[122:125]
	v_mfma_f32_16x16x32_bf16 v[114:117], v[160:163], v[200:203], v[114:117]
	v_mfma_f32_16x16x32_bf16 v[126:129], v[168:171], v[200:203], v[126:129]
	v_mfma_f32_16x16x32_bf16 v[62:65], v[148:151], v[180:183], v[62:65]
	v_mfma_f32_16x16x32_bf16 v[78:81], v[156:159], v[180:183], v[78:81]
	v_mfma_f32_16x16x32_bf16 v[70:73], v[148:151], v[188:191], v[70:73]
	v_mfma_f32_16x16x32_bf16 v[90:93], v[156:159], v[188:191], v[90:93]
	v_mfma_f32_16x16x32_bf16 v[82:85], v[148:151], v[196:199], v[82:85]
	v_mfma_f32_16x16x32_bf16 v[106:109], v[156:159], v[196:199], v[106:109]
	s_waitcnt lgkmcnt(0)
	v_mfma_f32_16x16x32_bf16 v[98:101], v[148:151], v[204:207], v[98:101]
	v_mfma_f32_16x16x32_bf16 v[118:121], v[156:159], v[204:207], v[118:121]
	v_mfma_f32_16x16x32_bf16 v[74:77], v[164:167], v[180:183], v[74:77]
	v_mfma_f32_16x16x32_bf16 v[94:97], v[172:175], v[180:183], v[94:97]
	v_mfma_f32_16x16x32_bf16 v[86:89], v[164:167], v[188:191], v[86:89]
	v_mfma_f32_16x16x32_bf16 v[110:113], v[172:175], v[188:191], v[110:113]
	v_mfma_f32_16x16x32_bf16 v[102:105], v[164:167], v[196:199], v[102:105]
	v_mfma_f32_16x16x32_bf16 v[122:125], v[172:175], v[196:199], v[122:125]
	v_mfma_f32_16x16x32_bf16 v[114:117], v[164:167], v[204:207], v[114:117]
	v_mfma_f32_16x16x32_bf16 v[126:129], v[172:175], v[204:207], v[126:129]
	s_setprio 0
	s_barrier
	s_add_i32 s83, s83, 2
	s_add_u32 s47, s47, 0x100
	s_addc_u32 s80, s80, 0
	s_add_u32 s81, s81, 0x100
	s_addc_u32 s82, s82, 0
	s_add_u32 s4, s4, 0x100
	s_addc_u32 s5, s5, 0
	s_cmp_gt_u32 s83, 29
	s_cbranch_scc1 .LBB0_869

; #define PG8_STAGE(bufoff, gbase, voff) do { _Pragma("unroll") for (int _i = 0; _i < 2; ++_i) { \
;         const unsigned m0v_ = (unsigned)(uintptr_t)(lds + (bufoff) + ldsw + _i * 8192); \
;         asm volatile("s_mov_b32 m0, %0\n\ts_nop 0\n\tglobal_load_lds_dwordx4 %1, %2\n\ts_nop 1" :: "s"(m0v_), "v"((voff)[_i]), "s"((const char*)(gbase)) : "m0", "memory"); } } while (0)
; #define PG8_LDA(dst, b, h) do { _Pragma("unroll") for (int m = 0; m < 4; ++m) _Pragma("unroll") for (int k = 0; k < 2; ++k) dst[m][k] = *(const LAS bf16x8*)(lds + PG8_SA(b, h) + aoff + m * 2048 + k * 1024); } while (0)
; #define PG8_LDB(dst, b, h) do { _Pragma("unroll") for (int n = 0; n < 2; ++n) _Pragma("unroll") for (int k = 0; k < 2; ++k) dst[n][k] = *(const LAS bf16x8*)(lds + PG8_SB(b, h) + boff + n * 2048 + k * 1024); } while (0)
; #define PG8_MMA(ai, bj, At, Bt) do { _Pragma("unroll") for (int m = 0; m < 4; ++m) _Pragma("unroll") for (int n = 0; n < 2; ++n) _Pragma("unroll") for (int k = 0; k < 2; ++k) \
;         acc[ai][bj][m][n] = __builtin_amdgcn_mfma_f32_16x16x32_bf16(Bt[n][k], At[m][k], acc[ai][bj][m][n], 0, 0, 0); } while (0)
; #define PG8_WAIT_V(n) asm volatile("s_waitcnt vmcnt(" #n ")" ::: "memory")
; #define PG8_WAIT_L(n) asm volatile("s_waitcnt lgkmcnt(" #n ")" ::: "memory")
; template <class Prob, class Epi, class Sched>
; __device__ __forceinline__ void gemm_phase(LAS unsigned char* lds, const Prob& P, const Sched& S, const Epi& E) {
;     ...
;             const char* a1 = cA + (size_t)(t + 1) * kstep;
;             const char* a2 = last ? nA : cA + (size_t)(t + 2) * kstep; const char* b2 = last ? nB : cB + (size_t)(t + 2) * kstep;
;             const char* a3 = a2 + kstep; const char* b3 = b2 + kstep;
;             PG8_LDB(B0, 0, 0); PG8_LDB(B1, 0, 1); PG8_SCHED; PG8_LDA(At, 0, 0); PG8_STAGE(PG8_SA(1, 1), a1 + hstepA, voffA);
;             PG8_WAIT_V(8); PG8_WAIT_L(0); PG8_BAR; __builtin_amdgcn_s_setprio(1); PG8_MMA(0, 0, At, B0); PG8_MMA(0, 1, At, B1); __builtin_amdgcn_s_setprio(0); PG8_BAR; PG8_SCHED;
;             PG8_LDA(At, 0, 1); PG8_STAGE(PG8_SB(0, 0), b2, voffB); PG8_STAGE(PG8_SB(0, 1), b2 + hstepB, voffB); PG8_STAGE(PG8_SA(0, 0), a2, voffA);
;             PG8_WAIT_V(8); PG8_WAIT_L(0); PG8_BAR; __builtin_amdgcn_s_setprio(1); PG8_MMA(1, 0, At, B0); PG8_MMA(1, 1, At, B1); __builtin_amdgcn_s_setprio(0); PG8_BAR; PG8_SCHED;
.LBB0_963:
	ds_read_b128 v[26:29], v199
	ds_read_b128 v[62:65], v199 offset:1024
	ds_read_b128 v[138:141], v199 offset:2048
	ds_read_b128 v[142:145], v199 offset:3072
	ds_read_b128 v[146:149], v200
	ds_read_b128 v[150:153], v200 offset:1024
	ds_read_b128 v[154:157], v200 offset:2048
	ds_read_b128 v[158:161], v200 offset:3072
	s_cmp_eq_u32 s65, 28
	s_cselect_b32 s54, s58, s49
	s_cselect_b32 s55, s59, s51
	s_cselect_b32 s8, s60, s63
	s_cselect_b32 s9, s61, s64
	s_add_u32 s6, s54, 0x80
	s_addc_u32 s7, s55, 0
	ds_read_b128 v[162:165], v201
	ds_read_b128 v[166:169], v201 offset:1024
	ds_read_b128 v[170:173], v201 offset:2048
	ds_read_b128 v[174:177], v201 offset:3072
	ds_read_b128 v[178:181], v201 offset:4096
	ds_read_b128 v[182:185], v201 offset:5120
	ds_read_b128 v[206:209], v201 offset:6144
	ds_read_b128 v[210:213], v201 offset:7168
	s_sub_u32 s98, s4, 0x80000
	s_subb_u32 s99, s5, 0
	s_mov_b32 m0, s76
	s_nop 0
	global_load_lds_dwordx4 v1, s[98:99]
	s_nop 1
	s_nop 0
	s_mov_b32 m0, s77
	s_nop 0
	global_load_lds_dwordx4 v197, s[98:99]
	s_nop 1
	s_mov_b32 m0, s81
	s_nop 0
	global_load_lds_dwordx4 v1, s[4:5]
	s_nop 1
	s_nop 0
	s_mov_b32 m0, s88
	s_nop 0
	global_load_lds_dwordx4 v197, s[4:5]
	s_nop 1
	s_waitcnt vmcnt(8)
	s_waitcnt lgkmcnt(0)
	s_barrier
	s_setprio 1
	s_waitcnt lgkmcnt(0)
	v_mfma_f32_16x16x32_bf16 v[134:137], v[26:29], v[162:165], v[134:137]
	v_mfma_f32_16x16x32_bf16 v[70:73], v[138:141], v[162:165], v[70:73]
	s_waitcnt lgkmcnt(5)
	v_mfma_f32_16x16x32_bf16 v[102:105], v[26:29], v[170:173], v[102:105]
	v_mfma_f32_16x16x32_bf16 v[82:85], v[138:141], v[170:173], v[82:85]
	s_waitcnt lgkmcnt(3)
	v_mfma_f32_16x16x32_bf16 v[78:81], v[26:29], v[178:181], v[78:81]
	v_mfma_f32_16x16x32_bf16 v[14:17], v[138:141], v[178:181], v[14:17]
	s_waitcnt lgkmcnt(1)
	v_mfma_f32_16x16x32_bf16 v[130:133], v[26:29], v[206:209], v[130:133]
	v_mfma_f32_16x16x32_bf16 v[126:129], v[138:141], v[206:209], v[126:129]
	v_mfma_f32_16x16x32_bf16 v[66:69], v[146:149], v[162:165], v[66:69]
	v_mfma_f32_16x16x32_bf16 v[54:57], v[154:157], v[162:165], v[54:57]
	v_mfma_f32_16x16x32_bf16 v[98:101], v[146:149], v[170:173], v[98:101]
	v_mfma_f32_16x16x32_bf16 v[86:89], v[154:157], v[170:173], v[86:89]
	v_mfma_f32_16x16x32_bf16 v[74:77], v[146:149], v[178:181], v[74:77]
	v_mfma_f32_16x16x32_bf16 v[10:13], v[154:157], v[178:181], v[10:13]
	v_mfma_f32_16x16x32_bf16 v[122:125], v[146:149], v[206:209], v[122:125]
	v_mfma_f32_16x16x32_bf16 v[58:61], v[154:157], v[206:209], v[58:61]
	v_mfma_f32_16x16x32_bf16 v[134:137], v[62:65], v[166:169], v[134:137]
	v_mfma_f32_16x16x32_bf16 v[70:73], v[142:145], v[166:169], v[70:73]
	v_mfma_f32_16x16x32_bf16 v[102:105], v[62:65], v[174:177], v[102:105]
	v_mfma_f32_16x16x32_bf16 v[82:85], v[142:145], v[174:177], v[82:85]
	v_mfma_f32_16x16x32_bf16 v[78:81], v[62:65], v[182:185], v[78:81]
	v_mfma_f32_16x16x32_bf16 v[14:17], v[142:145], v[182:185], v[14:17]
	s_waitcnt lgkmcnt(0)
	v_mfma_f32_16x16x32_bf16 v[130:133], v[62:65], v[210:213], v[130:133]
	v_mfma_f32_16x16x32_bf16 v[126:129], v[142:145], v[210:213], v[126:129]
	v_mfma_f32_16x16x32_bf16 v[66:69], v[150:153], v[166:169], v[66:69]
	v_mfma_f32_16x16x32_bf16 v[54:57], v[158:161], v[166:169], v[54:57]
	v_mfma_f32_16x16x32_bf16 v[98:101], v[150:153], v[174:177], v[98:101]
	v_mfma_f32_16x16x32_bf16 v[86:89], v[158:161], v[174:177], v[86:89]
	v_mfma_f32_16x16x32_bf16 v[74:77], v[150:153], v[182:185], v[74:77]
	v_mfma_f32_16x16x32_bf16 v[10:13], v[158:161], v[182:185], v[10:13]
	v_mfma_f32_16x16x32_bf16 v[122:125], v[150:153], v[210:213], v[122:125]
	v_mfma_f32_16x16x32_bf16 v[58:61], v[158:161], v[210:213], v[58:61]
	s_setprio 0
	s_barrier
	ds_read_b128 v[162:165], v201 offset:16384
	ds_read_b128 v[166:169], v201 offset:17408
	ds_read_b128 v[170:173], v201 offset:18432
	ds_read_b128 v[174:177], v201 offset:19456
	ds_read_b128 v[178:181], v201 offset:20480
	ds_read_b128 v[182:185], v201 offset:21504
	ds_read_b128 v[206:209], v201 offset:22528
	ds_read_b128 v[210:213], v201 offset:23552
	s_mov_b32 m0, s53
	s_nop 0
	global_load_lds_dwordx4 v196, s[8:9]
	s_nop 1
	s_add_u32 s90, s8, 0x80000
	s_mov_b32 m0, s56
	s_nop 0
	global_load_lds_dwordx4 v198, s[8:9]
	s_nop 1
	s_addc_u32 s91, s9, 0
	s_mov_b32 m0, s57
	s_nop 0
	global_load_lds_dwordx4 v196, s[90:91]
	s_nop 1
	s_nop 0
	s_mov_b32 m0, s66
	s_nop 0
	global_load_lds_dwordx4 v198, s[90:91]
	s_nop 1
	s_nop 0
	s_waitcnt vmcnt(6)
	s_waitcnt lgkmcnt(0)
	s_barrier
	s_setprio 1
	s_waitcnt lgkmcnt(0)
	v_mfma_f32_16x16x32_bf16 v[118:121], v[26:29], v[162:165], v[118:121]
	v_mfma_f32_16x16x32_bf16 v[30:33], v[138:141], v[162:165], v[30:33]
	s_waitcnt lgkmcnt(5)
	v_mfma_f32_16x16x32_bf16 v[42:45], v[26:29], v[170:173], v[42:45]
	v_mfma_f32_16x16x32_bf16 v[6:9], v[138:141], v[170:173], v[6:9]
	s_waitcnt lgkmcnt(3)
	v_mfma_f32_16x16x32_bf16 v[94:97], v[26:29], v[178:181], v[94:97]
	v_mfma_f32_16x16x32_bf16 v[46:49], v[138:141], v[178:181], v[46:49]
	s_waitcnt lgkmcnt(1)
	v_mfma_f32_16x16x32_bf16 v[26:29], v[26:29], v[206:209], v[114:117]
	v_mfma_f32_16x16x32_bf16 v[34:37], v[146:149], v[162:165], v[34:37]
	v_mfma_f32_16x16x32_bf16 v[18:21], v[154:157], v[162:165], v[18:21]
	v_mfma_f32_16x16x32_bf16 v[38:41], v[146:149], v[170:173], v[38:41]
	v_mfma_f32_16x16x32_bf16 v[2:5], v[154:157], v[170:173], v[2:5]
	v_mfma_f32_16x16x32_bf16 v[90:93], v[146:149], v[178:181], v[90:93]
	v_mfma_f32_16x16x32_bf16 v[50:53], v[154:157], v[178:181], v[50:53]
	v_mfma_f32_16x16x32_bf16 v[106:109], v[146:149], v[206:209], v[106:109]
	v_mfma_f32_16x16x32_bf16 v[22:25], v[154:157], v[206:209], v[22:25]
	v_mfma_f32_16x16x32_bf16 v[118:121], v[62:65], v[166:169], v[118:121]
	v_mfma_f32_16x16x32_bf16 v[30:33], v[142:145], v[166:169], v[30:33]
	v_mfma_f32_16x16x32_bf16 v[42:45], v[62:65], v[174:177], v[42:45]
	v_mfma_f32_16x16x32_bf16 v[6:9], v[142:145], v[174:177], v[6:9]
	v_mfma_f32_16x16x32_bf16 v[94:97], v[62:65], v[182:185], v[94:97]
	v_mfma_f32_16x16x32_bf16 v[46:49], v[142:145], v[182:185], v[46:49]
	s_waitcnt lgkmcnt(0)
	v_mfma_f32_16x16x32_bf16 v[26:29], v[62:65], v[210:213], v[26:29]
	v_mfma_f32_16x16x32_bf16 v[62:65], v[138:141], v[206:209], v[110:113]
	v_mfma_f32_16x16x32_bf16 v[34:37], v[150:153], v[166:169], v[34:37]
	v_mfma_f32_16x16x32_bf16 v[18:21], v[158:161], v[166:169], v[18:21]
	v_mfma_f32_16x16x32_bf16 v[38:41], v[150:153], v[174:177], v[38:41]
	v_mfma_f32_16x16x32_bf16 v[2:5], v[158:161], v[174:177], v[2:5]
	v_mfma_f32_16x16x32_bf16 v[90:93], v[150:153], v[182:185], v[90:93]
	v_mfma_f32_16x16x32_bf16 v[50:53], v[158:161], v[182:185], v[50:53]
	v_mfma_f32_16x16x32_bf16 v[106:109], v[150:153], v[210:213], v[106:109]
	v_mfma_f32_16x16x32_bf16 v[22:25], v[158:161], v[210:213], v[22:25]
	v_mfma_f32_16x16x32_bf16 v[62:65], v[142:145], v[210:213], v[62:65]
	s_setprio 0
	s_barrier
; #define PG8_STAGE(bufoff, gbase, voff) do { _Pragma("unroll") for (int _i = 0; _i < 2; ++_i) { \
;         const unsigned m0v_ = (unsigned)(uintptr_t)(lds + (bufoff) + ldsw + _i * 8192); \
;         asm volatile("s_mov_b32 m0, %0\n\ts_nop 0\n\tglobal_load_lds_dwordx4 %1, %2\n\ts_nop 1" :: "s"(m0v_), "v"((voff)[_i]), "s"((const char*)(gbase)) : "m0", "memory"); } } while (0)
; #define PG8_LDA(dst, b, h) do { _Pragma("unroll") for (int m = 0; m < 4; ++m) _Pragma("unroll") for (int k = 0; k < 2; ++k) dst[m][k] = *(const LAS bf16x8*)(lds + PG8_SA(b, h) + aoff + m * 2048 + k * 1024); } while (0)
; #define PG8_LDB(dst, b, h) do { _Pragma("unroll") for (int n = 0; n < 2; ++n) _Pragma("unroll") for (int k = 0; k < 2; ++k) dst[n][k] = *(const LAS bf16x8*)(lds + PG8_SB(b, h) + boff + n * 2048 + k * 1024); } while (0)
; #define PG8_MMA(ai, bj, At, Bt) do { _Pragma("unroll") for (int m = 0; m < 4; ++m) _Pragma("unroll") for (int n = 0; n < 2; ++n) _Pragma("unroll") for (int k = 0; k < 2; ++k) \
;         acc[ai][bj][m][n] = __builtin_amdgcn_mfma_f32_16x16x32_bf16(Bt[n][k], At[m][k], acc[ai][bj][m][n], 0, 0, 0); } while (0)
; #define PG8_WAIT_V(n) asm volatile("s_waitcnt vmcnt(" #n ")" ::: "memory")
; #define PG8_WAIT_L(n) asm volatile("s_waitcnt lgkmcnt(" #n ")" ::: "memory")
; #define PG8_BAR __builtin_amdgcn_s_barrier()
; #define PG8_SCHED __builtin_amdgcn_sched_barrier(0)
; template <class Prob, class Epi, class Sched>
; __device__ __forceinline__ void gemm_phase(LAS unsigned char* lds, const Prob& P, const Sched& S, const Epi& E) {
;     ...
;             PG8_LDB(B0, 1, 0); PG8_LDB(B1, 1, 1); PG8_SCHED; PG8_LDA(At, 1, 0); PG8_STAGE(PG8_SA(0, 1), a2 + hstepA, voffA);
;             PG8_WAIT_V(8); PG8_WAIT_L(0); PG8_BAR; __builtin_amdgcn_s_setprio(1); PG8_MMA(0, 0, At, B0); PG8_MMA(0, 1, At, B1); __builtin_amdgcn_s_setprio(0); PG8_BAR; PG8_SCHED;
;             PG8_LDA(At, 1, 1); PG8_STAGE(PG8_SB(1, 0), b3, voffB); PG8_STAGE(PG8_SB(1, 1), b3 + hstepB, voffB); PG8_STAGE(PG8_SA(1, 0), a3, voffA);
;             PG8_WAIT_V(8); PG8_WAIT_L(0); PG8_BAR; __builtin_amdgcn_s_setprio(1); PG8_MMA(1, 0, At, B0); PG8_MMA(1, 1, At, B1); __builtin_amdgcn_s_setprio(0); PG8_BAR; PG8_SCHED;
;         }
;         if (wr == 0) PG8_BAR;
	ds_read_b128 v[110:113], v202
	ds_read_b128 v[114:117], v202 offset:1024
	ds_read_b128 v[138:141], v202 offset:2048
	ds_read_b128 v[142:145], v202 offset:3072
	ds_read_b128 v[146:149], v203
	ds_read_b128 v[150:153], v203 offset:1024
	ds_read_b128 v[154:157], v203 offset:2048
	ds_read_b128 v[158:161], v203 offset:3072
	ds_read_b128 v[162:165], v201 offset:32768
	ds_read_b128 v[166:169], v201 offset:33792
	ds_read_b128 v[170:173], v201 offset:34816
	ds_read_b128 v[174:177], v201 offset:35840
	ds_read_b128 v[178:181], v201 offset:36864
	ds_read_b128 v[182:185], v201 offset:37888
	ds_read_b128 v[206:209], v201 offset:38912
	ds_read_b128 v[210:213], v201 offset:39936
	s_mov_b32 m0, s35
	s_nop 0
	global_load_lds_dwordx4 v1, s[54:55]
	s_nop 1
	s_nop 0
	s_mov_b32 m0, s67
	s_nop 0
	global_load_lds_dwordx4 v197, s[54:55]
	s_nop 1
	s_add_u32 s54, s54, 0x80000
	s_addc_u32 s55, s55, 0
	s_mov_b32 m0, s68
	s_nop 0
	global_load_lds_dwordx4 v1, s[54:55]
	s_nop 1
	s_nop 0
	s_mov_b32 m0, s69
	s_nop 0
	global_load_lds_dwordx4 v197, s[54:55]
	s_nop 1
	s_waitcnt vmcnt(8)
	s_waitcnt lgkmcnt(0)
	s_barrier
	s_setprio 1
	s_waitcnt lgkmcnt(0)
	v_mfma_f32_16x16x32_bf16 v[134:137], v[110:113], v[162:165], v[134:137]
	v_mfma_f32_16x16x32_bf16 v[70:73], v[138:141], v[162:165], v[70:73]
	s_waitcnt lgkmcnt(5)
	v_mfma_f32_16x16x32_bf16 v[102:105], v[110:113], v[170:173], v[102:105]
	v_mfma_f32_16x16x32_bf16 v[82:85], v[138:141], v[170:173], v[82:85]
	s_waitcnt lgkmcnt(3)
	v_mfma_f32_16x16x32_bf16 v[78:81], v[110:113], v[178:181], v[78:81]
	v_mfma_f32_16x16x32_bf16 v[14:17], v[138:141], v[178:181], v[14:17]
	s_waitcnt lgkmcnt(1)
	v_mfma_f32_16x16x32_bf16 v[130:133], v[110:113], v[206:209], v[130:133]
	v_mfma_f32_16x16x32_bf16 v[126:129], v[138:141], v[206:209], v[126:129]
	v_mfma_f32_16x16x32_bf16 v[66:69], v[146:149], v[162:165], v[66:69]
	v_mfma_f32_16x16x32_bf16 v[54:57], v[154:157], v[162:165], v[54:57]
	v_mfma_f32_16x16x32_bf16 v[98:101], v[146:149], v[170:173], v[98:101]
	v_mfma_f32_16x16x32_bf16 v[86:89], v[154:157], v[170:173], v[86:89]
	v_mfma_f32_16x16x32_bf16 v[74:77], v[146:149], v[178:181], v[74:77]
	v_mfma_f32_16x16x32_bf16 v[10:13], v[154:157], v[178:181], v[10:13]
	v_mfma_f32_16x16x32_bf16 v[122:125], v[146:149], v[206:209], v[122:125]
	v_mfma_f32_16x16x32_bf16 v[58:61], v[154:157], v[206:209], v[58:61]
	v_mfma_f32_16x16x32_bf16 v[134:137], v[114:117], v[166:169], v[134:137]
	v_mfma_f32_16x16x32_bf16 v[70:73], v[142:145], v[166:169], v[70:73]
	v_mfma_f32_16x16x32_bf16 v[102:105], v[114:117], v[174:177], v[102:105]
	v_mfma_f32_16x16x32_bf16 v[82:85], v[142:145], v[174:177], v[82:85]
	v_mfma_f32_16x16x32_bf16 v[78:81], v[114:117], v[182:185], v[78:81]
	v_mfma_f32_16x16x32_bf16 v[14:17], v[142:145], v[182:185], v[14:17]
	s_waitcnt lgkmcnt(0)
	v_mfma_f32_16x16x32_bf16 v[130:133], v[114:117], v[210:213], v[130:133]
	v_mfma_f32_16x16x32_bf16 v[126:129], v[142:145], v[210:213], v[126:129]
	v_mfma_f32_16x16x32_bf16 v[66:69], v[150:153], v[166:169], v[66:69]
	v_mfma_f32_16x16x32_bf16 v[54:57], v[158:161], v[166:169], v[54:57]
	v_mfma_f32_16x16x32_bf16 v[98:101], v[150:153], v[174:177], v[98:101]
	v_mfma_f32_16x16x32_bf16 v[86:89], v[158:161], v[174:177], v[86:89]
	v_mfma_f32_16x16x32_bf16 v[74:77], v[150:153], v[182:185], v[74:77]
	v_mfma_f32_16x16x32_bf16 v[10:13], v[158:161], v[182:185], v[10:13]
	v_mfma_f32_16x16x32_bf16 v[122:125], v[150:153], v[210:213], v[122:125]
	v_mfma_f32_16x16x32_bf16 v[58:61], v[158:161], v[210:213], v[58:61]
	s_setprio 0
	s_barrier
	ds_read_b128 v[162:165], v201 offset:49152
	ds_read_b128 v[166:169], v201 offset:50176
	ds_read_b128 v[170:173], v201 offset:51200
	ds_read_b128 v[174:177], v201 offset:52224
	ds_read_b128 v[178:181], v201 offset:53248
	ds_read_b128 v[182:185], v201 offset:54272
	ds_read_b128 v[206:209], v201 offset:55296
	ds_read_b128 v[210:213], v201 offset:56320
	s_add_u32 s54, s8, 0x80
	s_addc_u32 s55, s9, 0
	s_mov_b32 m0, s74
	s_nop 0
	global_load_lds_dwordx4 v196, s[54:55]
	s_nop 1
	s_add_u32 s8, s8, 0x80080
	s_mov_b32 m0, s75
	s_nop 0
	global_load_lds_dwordx4 v198, s[54:55]
	s_nop 1
	s_addc_u32 s9, s9, 0
	s_mov_b32 m0, s78
	s_nop 0
	global_load_lds_dwordx4 v196, s[8:9]
	s_nop 1
	s_nop 0
	s_mov_b32 m0, s79
	s_nop 0
	global_load_lds_dwordx4 v198, s[8:9]
	s_nop 1
	s_nop 0
	s_waitcnt vmcnt(6)
	s_waitcnt lgkmcnt(0)
	s_barrier
	s_setprio 1
	s_waitcnt lgkmcnt(0)
	v_mfma_f32_16x16x32_bf16 v[118:121], v[110:113], v[162:165], v[118:121]
	s_waitcnt lgkmcnt(5)
	v_mfma_f32_16x16x32_bf16 v[42:45], v[110:113], v[170:173], v[42:45]
	s_waitcnt lgkmcnt(3)
	v_mfma_f32_16x16x32_bf16 v[94:97], v[110:113], v[178:181], v[94:97]
	s_waitcnt lgkmcnt(1)
	v_mfma_f32_16x16x32_bf16 v[26:29], v[110:113], v[206:209], v[26:29]
	v_mfma_f32_16x16x32_bf16 v[118:121], v[114:117], v[166:169], v[118:121]
	v_mfma_f32_16x16x32_bf16 v[42:45], v[114:117], v[174:177], v[42:45]
	v_mfma_f32_16x16x32_bf16 v[94:97], v[114:117], v[182:185], v[94:97]
	s_waitcnt lgkmcnt(0)
	v_mfma_f32_16x16x32_bf16 v[114:117], v[114:117], v[210:213], v[26:29]
	v_mfma_f32_16x16x32_bf16 v[26:29], v[138:141], v[206:209], v[62:65]
	v_mfma_f32_16x16x32_bf16 v[110:113], v[142:145], v[210:213], v[26:29]
	v_mfma_f32_16x16x32_bf16 v[26:29], v[146:149], v[162:165], v[34:37]
	v_mfma_f32_16x16x32_bf16 v[34:37], v[150:153], v[166:169], v[26:29]
	v_mfma_f32_16x16x32_bf16 v[26:29], v[146:149], v[170:173], v[38:41]
	v_mfma_f32_16x16x32_bf16 v[38:41], v[150:153], v[174:177], v[26:29]
	v_mfma_f32_16x16x32_bf16 v[26:29], v[146:149], v[178:181], v[90:93]
	v_mfma_f32_16x16x32_bf16 v[90:93], v[150:153], v[182:185], v[26:29]
	v_mfma_f32_16x16x32_bf16 v[26:29], v[154:157], v[178:181], v[50:53]
	v_mfma_f32_16x16x32_bf16 v[30:33], v[138:141], v[162:165], v[30:33]
	v_mfma_f32_16x16x32_bf16 v[6:9], v[138:141], v[170:173], v[6:9]
	v_mfma_f32_16x16x32_bf16 v[46:49], v[138:141], v[178:181], v[46:49]
	v_mfma_f32_16x16x32_bf16 v[18:21], v[154:157], v[162:165], v[18:21]
	v_mfma_f32_16x16x32_bf16 v[2:5], v[154:157], v[170:173], v[2:5]
	v_mfma_f32_16x16x32_bf16 v[50:53], v[158:161], v[182:185], v[26:29]
	v_mfma_f32_16x16x32_bf16 v[26:29], v[146:149], v[206:209], v[106:109]
	v_mfma_f32_16x16x32_bf16 v[22:25], v[154:157], v[206:209], v[22:25]
	v_mfma_f32_16x16x32_bf16 v[30:33], v[142:145], v[166:169], v[30:33]
	v_mfma_f32_16x16x32_bf16 v[6:9], v[142:145], v[174:177], v[6:9]
	v_mfma_f32_16x16x32_bf16 v[46:49], v[142:145], v[182:185], v[46:49]
	v_mfma_f32_16x16x32_bf16 v[18:21], v[158:161], v[166:169], v[18:21]
	v_mfma_f32_16x16x32_bf16 v[2:5], v[158:161], v[174:177], v[2:5]
	v_mfma_f32_16x16x32_bf16 v[106:109], v[150:153], v[210:213], v[26:29]
	v_mfma_f32_16x16x32_bf16 v[22:25], v[158:161], v[210:213], v[22:25]
	s_setprio 0
	s_barrier
	s_add_i32 s65, s65, 2
	s_add_u32 s49, s49, 0x100
	s_addc_u32 s51, s51, 0
	s_add_u32 s63, s63, 0x100
	s_addc_u32 s64, s64, 0
	s_add_u32 s4, s4, 0x100
	s_addc_u32 s5, s5, 0
	s_cmp_gt_u32 s65, 29
	s_cbranch_scc0 .LBB0_963
	s_and_b64 vcc, exec, s[36:37]
	s_cbranch_vccz .LBB0_966
	s_barrier

; #define PG8_STAGE(bufoff, gbase, voff) do { _Pragma("unroll") for (int _i = 0; _i < 2; ++_i) { \
;         const unsigned m0v_ = (unsigned)(uintptr_t)(lds + (bufoff) + ldsw + _i * 8192); \
;         asm volatile("s_mov_b32 m0, %0\n\ts_nop 0\n\tglobal_load_lds_dwordx4 %1, %2\n\ts_nop 1" :: "s"(m0v_), "v"((voff)[_i]), "s"((const char*)(gbase)) : "m0", "memory"); } } while (0)
; #define PG8_LDA(dst, b, h) do { _Pragma("unroll") for (int m = 0; m < 4; ++m) _Pragma("unroll") for (int k = 0; k < 2; ++k) dst[m][k] = *(const LAS bf16x8*)(lds + PG8_SA(b, h) + aoff + m * 2048 + k * 1024); } while (0)
; #define PG8_LDB(dst, b, h) do { _Pragma("unroll") for (int n = 0; n < 2; ++n) _Pragma("unroll") for (int k = 0; k < 2; ++k) dst[n][k] = *(const LAS bf16x8*)(lds + PG8_SB(b, h) + boff + n * 2048 + k * 1024); } while (0)
; #define PG8_MMA(ai, bj, At, Bt) do { _Pragma("unroll") for (int m = 0; m < 4; ++m) _Pragma("unroll") for (int n = 0; n < 2; ++n) _Pragma("unroll") for (int k = 0; k < 2; ++k) \
;         acc[ai][bj][m][n] = __builtin_amdgcn_mfma_f32_16x16x32_bf16(Bt[n][k], At[m][k], acc[ai][bj][m][n], 0, 0, 0); } while (0)
; #define PG8_WAIT_V(n) asm volatile("s_waitcnt vmcnt(" #n ")" ::: "memory")
; #define PG8_WAIT_L(n) asm volatile("s_waitcnt lgkmcnt(" #n ")" ::: "memory")
; template <class Prob, class Epi, class Sched>
; __device__ __forceinline__ void gemm_phase(LAS unsigned char* lds, const Prob& P, const Sched& S, const Epi& E) {
;     ...
;             const char* a1 = cA + (size_t)(t + 1) * kstep;
;             const char* a2 = last ? nA : cA + (size_t)(t + 2) * kstep; const char* b2 = last ? nB : cB + (size_t)(t + 2) * kstep;
;             const char* a3 = a2 + kstep; const char* b3 = b2 + kstep;
;             PG8_LDB(B0, 0, 0); PG8_LDB(B1, 0, 1); PG8_SCHED; PG8_LDA(At, 0, 0); PG8_STAGE(PG8_SA(1, 1), a1 + hstepA, voffA);
;             PG8_WAIT_V(8); PG8_WAIT_L(0); PG8_BAR; __builtin_amdgcn_s_setprio(1); PG8_MMA(0, 0, At, B0); PG8_MMA(0, 1, At, B1); __builtin_amdgcn_s_setprio(0); PG8_BAR; PG8_SCHED;
;             PG8_LDA(At, 0, 1); PG8_STAGE(PG8_SB(0, 0), b2, voffB); PG8_STAGE(PG8_SB(0, 1), b2 + hstepB, voffB); PG8_STAGE(PG8_SA(0, 0), a2, voffA);
;             PG8_WAIT_V(8); PG8_WAIT_L(0); PG8_BAR; __builtin_amdgcn_s_setprio(1); PG8_MMA(1, 0, At, B0); PG8_MMA(1, 1, At, B1); __builtin_amdgcn_s_setprio(0); PG8_BAR; PG8_SCHED;
.LBB0_1159:
	v_add_u32_e32 v142, 0x10000, v168
	v_add_u32_e32 v146, 0x14000, v168
	s_add_u32 s6, s2, s4
	ds_read_b128 v[130:133], v142
	ds_read_b128 v[134:137], v142 offset:1024
	ds_read_b128 v[138:141], v142 offset:2048
	ds_read_b128 v[142:145], v142 offset:3072
	ds_read_b128 v[148:151], v146
	ds_read_b128 v[164:167], v146 offset:1024
	ds_read_b128 v[174:177], v146 offset:2048
	ds_read_b128 v[178:181], v146 offset:3072
	s_addc_u32 s7, s3, s5
	s_cmpk_eq_i32 s37, 0x54
	s_cselect_b32 s42, s34, s6
	s_cselect_b32 s43, s35, s7
	s_cselect_b32 s39, 0, s4
	s_cselect_b32 s41, 0, s5
	s_add_u32 s6, s42, 0x80
	s_addc_u32 s7, s43, 0
	s_add_u32 s40, s16, s39
	s_addc_u32 s41, s17, s41
	ds_read_b128 v[182:185], v169
	ds_read_b128 v[186:189], v169 offset:1024
	ds_read_b128 v[190:193], v169 offset:2048
	ds_read_b128 v[194:197], v169 offset:3072
	ds_read_b128 v[198:201], v169 offset:4096
	ds_read_b128 v[202:205], v169 offset:5120
	ds_read_b128 v[206:209], v169 offset:6144
	ds_read_b128 v[210:213], v169 offset:7168
	s_add_u32 s39, s10, s4
	s_addc_u32 s45, s31, s5
	s_add_u32 s44, s39, 0xffffff80
	s_addc_u32 s45, s45, -1
	s_sub_u32 s98, s44, 0x160000
	s_subb_u32 s99, s45, 0
	s_mov_b32 m0, s63
	s_nop 0
	global_load_lds_dwordx4 v155, s[98:99]
	s_nop 1
	s_nop 0
	s_mov_b32 m0, s64
	s_nop 0
	global_load_lds_dwordx4 v161, s[98:99]
	s_nop 1
	s_mov_b32 m0, s67
	s_nop 0
	global_load_lds_dwordx4 v155, s[44:45]
	s_nop 1
	s_nop 0
	s_mov_b32 m0, s70
	s_nop 0
	global_load_lds_dwordx4 v161, s[44:45]
	s_nop 1
	s_waitcnt vmcnt(8)
	s_waitcnt lgkmcnt(0)
	s_barrier
	s_setprio 1
	s_waitcnt lgkmcnt(7)
	v_mfma_f32_16x16x32_bf16 v[2:5], v[130:133], v[182:185], v[2:5]
	v_mfma_f32_16x16x32_bf16 v[18:21], v[138:141], v[182:185], v[18:21]
	s_waitcnt lgkmcnt(5)
	v_mfma_f32_16x16x32_bf16 v[26:29], v[130:133], v[190:193], v[26:29]
	v_mfma_f32_16x16x32_bf16 v[38:41], v[138:141], v[190:193], v[38:41]
	s_waitcnt lgkmcnt(3)
	v_mfma_f32_16x16x32_bf16 v[6:9], v[130:133], v[198:201], v[6:9]
	v_mfma_f32_16x16x32_bf16 v[14:17], v[138:141], v[198:201], v[14:17]
	s_waitcnt lgkmcnt(1)
	v_mfma_f32_16x16x32_bf16 v[10:13], v[130:133], v[206:209], v[10:13]
	v_mfma_f32_16x16x32_bf16 v[22:25], v[138:141], v[206:209], v[22:25]
	v_mfma_f32_16x16x32_bf16 v[62:65], v[148:151], v[182:185], v[62:65]
	v_mfma_f32_16x16x32_bf16 v[94:97], v[174:177], v[182:185], v[94:97]
	v_mfma_f32_16x16x32_bf16 v[30:33], v[148:151], v[190:193], v[30:33]
	v_mfma_f32_16x16x32_bf16 v[46:49], v[174:177], v[190:193], v[46:49]
	v_mfma_f32_16x16x32_bf16 v[34:37], v[148:151], v[198:201], v[34:37]
	v_mfma_f32_16x16x32_bf16 v[54:57], v[174:177], v[198:201], v[54:57]
	v_mfma_f32_16x16x32_bf16 v[42:45], v[148:151], v[206:209], v[42:45]
	v_mfma_f32_16x16x32_bf16 v[58:61], v[174:177], v[206:209], v[58:61]
	v_mfma_f32_16x16x32_bf16 v[2:5], v[134:137], v[186:189], v[2:5]
	v_mfma_f32_16x16x32_bf16 v[18:21], v[142:145], v[186:189], v[18:21]
	v_mfma_f32_16x16x32_bf16 v[26:29], v[134:137], v[194:197], v[26:29]
	v_mfma_f32_16x16x32_bf16 v[38:41], v[142:145], v[194:197], v[38:41]
	v_mfma_f32_16x16x32_bf16 v[6:9], v[134:137], v[202:205], v[6:9]
	v_mfma_f32_16x16x32_bf16 v[14:17], v[142:145], v[202:205], v[14:17]
	s_waitcnt lgkmcnt(0)
	v_mfma_f32_16x16x32_bf16 v[10:13], v[134:137], v[210:213], v[10:13]
	v_mfma_f32_16x16x32_bf16 v[22:25], v[142:145], v[210:213], v[22:25]
	v_mfma_f32_16x16x32_bf16 v[62:65], v[164:167], v[186:189], v[62:65]
	v_mfma_f32_16x16x32_bf16 v[94:97], v[178:181], v[186:189], v[94:97]
	v_mfma_f32_16x16x32_bf16 v[30:33], v[164:167], v[194:197], v[30:33]
	v_mfma_f32_16x16x32_bf16 v[46:49], v[178:181], v[194:197], v[46:49]
	v_mfma_f32_16x16x32_bf16 v[34:37], v[164:167], v[202:205], v[34:37]
	v_mfma_f32_16x16x32_bf16 v[54:57], v[178:181], v[202:205], v[54:57]
	v_mfma_f32_16x16x32_bf16 v[42:45], v[164:167], v[210:213], v[42:45]
	v_mfma_f32_16x16x32_bf16 v[58:61], v[178:181], v[210:213], v[58:61]
	s_setprio 0
	s_barrier
	ds_read_b128 v[182:185], v169 offset:16384
	ds_read_b128 v[186:189], v169 offset:17408
	ds_read_b128 v[190:193], v169 offset:18432
	ds_read_b128 v[194:197], v169 offset:19456
	ds_read_b128 v[198:201], v169 offset:20480
	ds_read_b128 v[202:205], v169 offset:21504
	ds_read_b128 v[206:209], v169 offset:22528
	ds_read_b128 v[210:213], v169 offset:23552
	s_mov_b32 m0, s50
	s_nop 0
	global_load_lds_dwordx4 v159, s[40:41]
	s_nop 1
	s_add_u32 s44, s40, 0x160000
	s_mov_b32 m0, s51
	s_nop 0
	global_load_lds_dwordx4 v163, s[40:41]
	s_nop 1
	s_addc_u32 s45, s41, 0
	s_mov_b32 m0, s52
	s_nop 0
	global_load_lds_dwordx4 v159, s[44:45]
	s_nop 1
	s_nop 0
	s_mov_b32 m0, s53
	s_nop 0
	global_load_lds_dwordx4 v163, s[44:45]
	s_nop 1
	s_nop 0
	s_waitcnt vmcnt(6)
	s_waitcnt lgkmcnt(0)
	s_barrier
; #define PG8_STAGE(bufoff, gbase, voff) do { _Pragma("unroll") for (int _i = 0; _i < 2; ++_i) { \
;         const unsigned m0v_ = (unsigned)(uintptr_t)(lds + (bufoff) + ldsw + _i * 8192); \
;         asm volatile("s_mov_b32 m0, %0\n\ts_nop 0\n\tglobal_load_lds_dwordx4 %1, %2\n\ts_nop 1" :: "s"(m0v_), "v"((voff)[_i]), "s"((const char*)(gbase)) : "m0", "memory"); } } while (0)
; #define PG8_LDA(dst, b, h) do { _Pragma("unroll") for (int m = 0; m < 4; ++m) _Pragma("unroll") for (int k = 0; k < 2; ++k) dst[m][k] = *(const LAS bf16x8*)(lds + PG8_SA(b, h) + aoff + m * 2048 + k * 1024); } while (0)
; #define PG8_LDB(dst, b, h) do { _Pragma("unroll") for (int n = 0; n < 2; ++n) _Pragma("unroll") for (int k = 0; k < 2; ++k) dst[n][k] = *(const LAS bf16x8*)(lds + PG8_SB(b, h) + boff + n * 2048 + k * 1024); } while (0)
; #define PG8_MMA(ai, bj, At, Bt) do { _Pragma("unroll") for (int m = 0; m < 4; ++m) _Pragma("unroll") for (int n = 0; n < 2; ++n) _Pragma("unroll") for (int k = 0; k < 2; ++k) \
;         acc[ai][bj][m][n] = __builtin_amdgcn_mfma_f32_16x16x32_bf16(Bt[n][k], At[m][k], acc[ai][bj][m][n], 0, 0, 0); } while (0)
; #define PG8_WAIT_V(n) asm volatile("s_waitcnt vmcnt(" #n ")" ::: "memory")
; #define PG8_WAIT_L(n) asm volatile("s_waitcnt lgkmcnt(" #n ")" ::: "memory")
; #define PG8_BAR __builtin_amdgcn_s_barrier()
; #define PG8_SCHED __builtin_amdgcn_sched_barrier(0)
; template <class Prob, class Epi, class Sched>
; __device__ __forceinline__ void gemm_phase(LAS unsigned char* lds, const Prob& P, const Sched& S, const Epi& E) {
;     ...
;             PG8_WAIT_V(8); PG8_WAIT_L(0); PG8_BAR; __builtin_amdgcn_s_setprio(1); PG8_MMA(1, 0, At, B0); PG8_MMA(1, 1, At, B1); __builtin_amdgcn_s_setprio(0); PG8_BAR; PG8_SCHED;
;             PG8_LDB(B0, 1, 0); PG8_LDB(B1, 1, 1); PG8_SCHED; PG8_LDA(At, 1, 0); PG8_STAGE(PG8_SA(0, 1), a2 + hstepA, voffA);
;             PG8_WAIT_V(8); PG8_WAIT_L(0); PG8_BAR; __builtin_amdgcn_s_setprio(1); PG8_MMA(0, 0, At, B0); PG8_MMA(0, 1, At, B1); __builtin_amdgcn_s_setprio(0); PG8_BAR; PG8_SCHED;
	s_setprio 1
	s_waitcnt lgkmcnt(7)
	v_mfma_f32_16x16x32_bf16 v[78:81], v[130:133], v[182:185], v[78:81]
	v_mfma_f32_16x16x32_bf16 v[90:93], v[138:141], v[182:185], v[90:93]
	s_waitcnt lgkmcnt(5)
	v_mfma_f32_16x16x32_bf16 v[74:77], v[130:133], v[190:193], v[74:77]
	v_mfma_f32_16x16x32_bf16 v[86:89], v[138:141], v[190:193], v[86:89]
	s_waitcnt lgkmcnt(3)
	v_mfma_f32_16x16x32_bf16 v[70:73], v[130:133], v[198:201], v[70:73]
	v_mfma_f32_16x16x32_bf16 v[82:85], v[138:141], v[198:201], v[82:85]
	s_waitcnt lgkmcnt(1)
	v_mfma_f32_16x16x32_bf16 v[66:69], v[130:133], v[206:209], v[66:69]
	v_mfma_f32_16x16x32_bf16 v[50:53], v[138:141], v[206:209], v[50:53]
	v_mfma_f32_16x16x32_bf16 v[114:117], v[148:151], v[182:185], v[114:117]
	v_mfma_f32_16x16x32_bf16 v[126:129], v[174:177], v[182:185], v[126:129]
	v_mfma_f32_16x16x32_bf16 v[110:113], v[148:151], v[190:193], v[110:113]
	v_mfma_f32_16x16x32_bf16 v[122:125], v[174:177], v[190:193], v[122:125]
	v_mfma_f32_16x16x32_bf16 v[106:109], v[148:151], v[198:201], v[106:109]
	v_mfma_f32_16x16x32_bf16 v[118:121], v[174:177], v[198:201], v[118:121]
	v_mfma_f32_16x16x32_bf16 v[102:105], v[148:151], v[206:209], v[102:105]
	v_mfma_f32_16x16x32_bf16 v[98:101], v[174:177], v[206:209], v[98:101]
	v_mfma_f32_16x16x32_bf16 v[78:81], v[134:137], v[186:189], v[78:81]
	v_mfma_f32_16x16x32_bf16 v[90:93], v[142:145], v[186:189], v[90:93]
	v_mfma_f32_16x16x32_bf16 v[74:77], v[134:137], v[194:197], v[74:77]
	v_mfma_f32_16x16x32_bf16 v[86:89], v[142:145], v[194:197], v[86:89]
	v_mfma_f32_16x16x32_bf16 v[70:73], v[134:137], v[202:205], v[70:73]
	v_mfma_f32_16x16x32_bf16 v[82:85], v[142:145], v[202:205], v[82:85]
	s_waitcnt lgkmcnt(0)
	v_mfma_f32_16x16x32_bf16 v[66:69], v[134:137], v[210:213], v[66:69]
	v_mfma_f32_16x16x32_bf16 v[50:53], v[142:145], v[210:213], v[50:53]
	v_mfma_f32_16x16x32_bf16 v[114:117], v[164:167], v[186:189], v[114:117]
	v_mfma_f32_16x16x32_bf16 v[126:129], v[178:181], v[186:189], v[126:129]
	v_mfma_f32_16x16x32_bf16 v[110:113], v[164:167], v[194:197], v[110:113]
	v_mfma_f32_16x16x32_bf16 v[122:125], v[178:181], v[194:197], v[122:125]
	v_mfma_f32_16x16x32_bf16 v[106:109], v[164:167], v[202:205], v[106:109]
	v_mfma_f32_16x16x32_bf16 v[118:121], v[178:181], v[202:205], v[118:121]
	v_mfma_f32_16x16x32_bf16 v[102:105], v[164:167], v[210:213], v[102:105]
	v_mfma_f32_16x16x32_bf16 v[98:101], v[178:181], v[210:213], v[98:101]
	s_setprio 0
	s_barrier
	v_add_u32_e32 v142, 0x18000, v168
	v_add_u32_e32 v146, 0x1c000, v168
	ds_read_b128 v[130:133], v142
	ds_read_b128 v[134:137], v142 offset:1024
	ds_read_b128 v[138:141], v142 offset:2048
	ds_read_b128 v[142:145], v142 offset:3072
	ds_read_b128 v[148:151], v146
	ds_read_b128 v[164:167], v146 offset:1024
	ds_read_b128 v[174:177], v146 offset:2048
	ds_read_b128 v[178:181], v146 offset:3072
	ds_read_b128 v[182:185], v169 offset:32768
	ds_read_b128 v[186:189], v169 offset:33792
	ds_read_b128 v[190:193], v169 offset:34816
	ds_read_b128 v[194:197], v169 offset:35840
	ds_read_b128 v[198:201], v169 offset:36864
	ds_read_b128 v[202:205], v169 offset:37888
	ds_read_b128 v[206:209], v169 offset:38912
	ds_read_b128 v[210:213], v169 offset:39936
	s_mov_b32 m0, s9
	s_nop 0
	global_load_lds_dwordx4 v155, s[42:43]
	s_nop 1
	s_nop 0
	s_mov_b32 m0, s54
	s_nop 0
	global_load_lds_dwordx4 v161, s[42:43]
	s_nop 1
	s_add_u32 s42, s42, 0x160000
	s_addc_u32 s43, s43, 0
	s_mov_b32 m0, s55
	s_nop 0
	global_load_lds_dwordx4 v155, s[42:43]
	s_nop 1
	s_nop 0
	s_mov_b32 m0, s56
	s_nop 0
	global_load_lds_dwordx4 v161, s[42:43]
	s_nop 1
	s_waitcnt vmcnt(8)
	s_waitcnt lgkmcnt(0)
	s_barrier
; #define PG8_STAGE(bufoff, gbase, voff) do { _Pragma("unroll") for (int _i = 0; _i < 2; ++_i) { \
;         const unsigned m0v_ = (unsigned)(uintptr_t)(lds + (bufoff) + ldsw + _i * 8192); \
;         asm volatile("s_mov_b32 m0, %0\n\ts_nop 0\n\tglobal_load_lds_dwordx4 %1, %2\n\ts_nop 1" :: "s"(m0v_), "v"((voff)[_i]), "s"((const char*)(gbase)) : "m0", "memory"); } } while (0)
; #define PG8_LDA(dst, b, h) do { _Pragma("unroll") for (int m = 0; m < 4; ++m) _Pragma("unroll") for (int k = 0; k < 2; ++k) dst[m][k] = *(const LAS bf16x8*)(lds + PG8_SA(b, h) + aoff + m * 2048 + k * 1024); } while (0)
; #define PG8_MMA(ai, bj, At, Bt) do { _Pragma("unroll") for (int m = 0; m < 4; ++m) _Pragma("unroll") for (int n = 0; n < 2; ++n) _Pragma("unroll") for (int k = 0; k < 2; ++k) \
;         acc[ai][bj][m][n] = __builtin_amdgcn_mfma_f32_16x16x32_bf16(Bt[n][k], At[m][k], acc[ai][bj][m][n], 0, 0, 0); } while (0)
; #define PG8_WAIT_V(n) asm volatile("s_waitcnt vmcnt(" #n ")" ::: "memory")
; #define PG8_WAIT_L(n) asm volatile("s_waitcnt lgkmcnt(" #n ")" ::: "memory")
; #define PG8_BAR __builtin_amdgcn_s_barrier()
; #define PG8_SCHED __builtin_amdgcn_sched_barrier(0)
; template <class Prob, class Epi, class Sched>
; __device__ __forceinline__ void gemm_phase(LAS unsigned char* lds, const Prob& P, const Sched& S, const Epi& E) {
;     ...
;             PG8_WAIT_V(8); PG8_WAIT_L(0); PG8_BAR; __builtin_amdgcn_s_setprio(1); PG8_MMA(0, 0, At, B0); PG8_MMA(0, 1, At, B1); __builtin_amdgcn_s_setprio(0); PG8_BAR; PG8_SCHED;
;             PG8_LDA(At, 1, 1); PG8_STAGE(PG8_SB(1, 0), b3, voffB); PG8_STAGE(PG8_SB(1, 1), b3 + hstepB, voffB); PG8_STAGE(PG8_SA(1, 0), a3, voffA);
;             PG8_WAIT_V(8); PG8_WAIT_L(0); PG8_BAR; __builtin_amdgcn_s_setprio(1); PG8_MMA(1, 0, At, B0); PG8_MMA(1, 1, At, B1); __builtin_amdgcn_s_setprio(0); PG8_BAR; PG8_SCHED;
;         }
;         if (wr == 0) PG8_BAR;
	s_setprio 1
	s_waitcnt lgkmcnt(7)
	v_mfma_f32_16x16x32_bf16 v[2:5], v[130:133], v[182:185], v[2:5]
	v_mfma_f32_16x16x32_bf16 v[18:21], v[138:141], v[182:185], v[18:21]
	s_waitcnt lgkmcnt(5)
	v_mfma_f32_16x16x32_bf16 v[26:29], v[130:133], v[190:193], v[26:29]
	v_mfma_f32_16x16x32_bf16 v[38:41], v[138:141], v[190:193], v[38:41]
	s_waitcnt lgkmcnt(3)
	v_mfma_f32_16x16x32_bf16 v[6:9], v[130:133], v[198:201], v[6:9]
	v_mfma_f32_16x16x32_bf16 v[14:17], v[138:141], v[198:201], v[14:17]
	s_waitcnt lgkmcnt(1)
	v_mfma_f32_16x16x32_bf16 v[10:13], v[130:133], v[206:209], v[10:13]
	v_mfma_f32_16x16x32_bf16 v[22:25], v[138:141], v[206:209], v[22:25]
	v_mfma_f32_16x16x32_bf16 v[62:65], v[148:151], v[182:185], v[62:65]
	v_mfma_f32_16x16x32_bf16 v[94:97], v[174:177], v[182:185], v[94:97]
	v_mfma_f32_16x16x32_bf16 v[30:33], v[148:151], v[190:193], v[30:33]
	v_mfma_f32_16x16x32_bf16 v[46:49], v[174:177], v[190:193], v[46:49]
	v_mfma_f32_16x16x32_bf16 v[34:37], v[148:151], v[198:201], v[34:37]
	v_mfma_f32_16x16x32_bf16 v[54:57], v[174:177], v[198:201], v[54:57]
	v_mfma_f32_16x16x32_bf16 v[42:45], v[148:151], v[206:209], v[42:45]
	v_mfma_f32_16x16x32_bf16 v[58:61], v[174:177], v[206:209], v[58:61]
	v_mfma_f32_16x16x32_bf16 v[2:5], v[134:137], v[186:189], v[2:5]
	v_mfma_f32_16x16x32_bf16 v[18:21], v[142:145], v[186:189], v[18:21]
	v_mfma_f32_16x16x32_bf16 v[26:29], v[134:137], v[194:197], v[26:29]
	v_mfma_f32_16x16x32_bf16 v[38:41], v[142:145], v[194:197], v[38:41]
	v_mfma_f32_16x16x32_bf16 v[6:9], v[134:137], v[202:205], v[6:9]
	v_mfma_f32_16x16x32_bf16 v[14:17], v[142:145], v[202:205], v[14:17]
	s_waitcnt lgkmcnt(0)
	v_mfma_f32_16x16x32_bf16 v[10:13], v[134:137], v[210:213], v[10:13]
	v_mfma_f32_16x16x32_bf16 v[22:25], v[142:145], v[210:213], v[22:25]
	v_mfma_f32_16x16x32_bf16 v[62:65], v[164:167], v[186:189], v[62:65]
	v_mfma_f32_16x16x32_bf16 v[94:97], v[178:181], v[186:189], v[94:97]
	v_mfma_f32_16x16x32_bf16 v[30:33], v[164:167], v[194:197], v[30:33]
	v_mfma_f32_16x16x32_bf16 v[46:49], v[178:181], v[194:197], v[46:49]
	v_mfma_f32_16x16x32_bf16 v[34:37], v[164:167], v[202:205], v[34:37]
	v_mfma_f32_16x16x32_bf16 v[54:57], v[178:181], v[202:205], v[54:57]
	v_mfma_f32_16x16x32_bf16 v[42:45], v[164:167], v[210:213], v[42:45]
	v_mfma_f32_16x16x32_bf16 v[58:61], v[178:181], v[210:213], v[58:61]
	s_setprio 0
	s_barrier
	ds_read_b128 v[182:185], v169 offset:49152
	ds_read_b128 v[186:189], v169 offset:50176
	ds_read_b128 v[190:193], v169 offset:51200
	ds_read_b128 v[194:197], v169 offset:52224
	ds_read_b128 v[198:201], v169 offset:53248
	ds_read_b128 v[202:205], v169 offset:54272
	ds_read_b128 v[206:209], v169 offset:55296
	ds_read_b128 v[210:213], v169 offset:56320
	s_add_u32 s42, s40, 0x80
	s_addc_u32 s43, s41, 0
	s_mov_b32 m0, s61
	s_nop 0
	global_load_lds_dwordx4 v159, s[42:43]
	s_nop 1
	s_add_u32 s40, s40, 0x160080
	s_mov_b32 m0, s62
	s_nop 0
	global_load_lds_dwordx4 v163, s[42:43]
	s_nop 1
	s_addc_u32 s41, s41, 0
	s_mov_b32 m0, s65
	s_nop 0
	global_load_lds_dwordx4 v159, s[40:41]
	s_nop 1
	s_nop 0
	s_mov_b32 m0, s66
	s_nop 0
	global_load_lds_dwordx4 v163, s[40:41]
	s_nop 1
	s_nop 0
	s_waitcnt vmcnt(6)
	s_waitcnt lgkmcnt(0)
	s_barrier
	s_setprio 1
	s_waitcnt lgkmcnt(7)
	v_mfma_f32_16x16x32_bf16 v[78:81], v[130:133], v[182:185], v[78:81]
	v_mfma_f32_16x16x32_bf16 v[90:93], v[138:141], v[182:185], v[90:93]
	s_waitcnt lgkmcnt(5)
	v_mfma_f32_16x16x32_bf16 v[74:77], v[130:133], v[190:193], v[74:77]
	v_mfma_f32_16x16x32_bf16 v[86:89], v[138:141], v[190:193], v[86:89]
	s_waitcnt lgkmcnt(3)
	v_mfma_f32_16x16x32_bf16 v[70:73], v[130:133], v[198:201], v[70:73]
	v_mfma_f32_16x16x32_bf16 v[82:85], v[138:141], v[198:201], v[82:85]
	s_waitcnt lgkmcnt(1)
	v_mfma_f32_16x16x32_bf16 v[66:69], v[130:133], v[206:209], v[66:69]
	v_mfma_f32_16x16x32_bf16 v[50:53], v[138:141], v[206:209], v[50:53]
	v_mfma_f32_16x16x32_bf16 v[114:117], v[148:151], v[182:185], v[114:117]
	v_mfma_f32_16x16x32_bf16 v[126:129], v[174:177], v[182:185], v[126:129]
	v_mfma_f32_16x16x32_bf16 v[110:113], v[148:151], v[190:193], v[110:113]
	v_mfma_f32_16x16x32_bf16 v[122:125], v[174:177], v[190:193], v[122:125]
	v_mfma_f32_16x16x32_bf16 v[106:109], v[148:151], v[198:201], v[106:109]
	v_mfma_f32_16x16x32_bf16 v[118:121], v[174:177], v[198:201], v[118:121]
	v_mfma_f32_16x16x32_bf16 v[102:105], v[148:151], v[206:209], v[102:105]
	v_mfma_f32_16x16x32_bf16 v[98:101], v[174:177], v[206:209], v[98:101]
	v_mfma_f32_16x16x32_bf16 v[78:81], v[134:137], v[186:189], v[78:81]
	v_mfma_f32_16x16x32_bf16 v[90:93], v[142:145], v[186:189], v[90:93]
	v_mfma_f32_16x16x32_bf16 v[74:77], v[134:137], v[194:197], v[74:77]
	v_mfma_f32_16x16x32_bf16 v[86:89], v[142:145], v[194:197], v[86:89]
	v_mfma_f32_16x16x32_bf16 v[70:73], v[134:137], v[202:205], v[70:73]
	v_mfma_f32_16x16x32_bf16 v[82:85], v[142:145], v[202:205], v[82:85]
	s_waitcnt lgkmcnt(0)
	v_mfma_f32_16x16x32_bf16 v[66:69], v[134:137], v[210:213], v[66:69]
	v_mfma_f32_16x16x32_bf16 v[50:53], v[142:145], v[210:213], v[50:53]
	v_mfma_f32_16x16x32_bf16 v[114:117], v[164:167], v[186:189], v[114:117]
	v_mfma_f32_16x16x32_bf16 v[126:129], v[178:181], v[186:189], v[126:129]
	v_mfma_f32_16x16x32_bf16 v[110:113], v[164:167], v[194:197], v[110:113]
	v_mfma_f32_16x16x32_bf16 v[122:125], v[178:181], v[194:197], v[122:125]
	v_mfma_f32_16x16x32_bf16 v[106:109], v[164:167], v[202:205], v[106:109]
	v_mfma_f32_16x16x32_bf16 v[118:121], v[178:181], v[202:205], v[118:121]
	v_mfma_f32_16x16x32_bf16 v[102:105], v[164:167], v[210:213], v[102:105]
	v_mfma_f32_16x16x32_bf16 v[98:101], v[178:181], v[210:213], v[98:101]
	s_setprio 0
	s_barrier
	s_add_i32 s37, s37, 2
	s_add_u32 s4, s4, 0x100
	s_addc_u32 s5, s5, 0
	s_cmpk_gt_u32 s37, 0x55
	s_cbranch_scc0 .LBB0_1159
	s_and_b64 vcc, exec, s[20:21]
	s_cbranch_vccz .LBB0_1162
	s_barrier

; __global__ void __launch_bounds__(512, 2) hymba_fwd(Args args) {
	.amdhsa_kernel _Z9hymba_fwd4Args
		.amdhsa_group_segment_fixed_size 0
		.amdhsa_private_segment_fixed_size 0
		.amdhsa_kernarg_size 416
		.amdhsa_user_sgpr_count 2
		.amdhsa_user_sgpr_dispatch_ptr 0
		.amdhsa_user_sgpr_queue_ptr 0
		.amdhsa_user_sgpr_kernarg_segment_ptr 1
		.amdhsa_user_sgpr_dispatch_id 0
		.amdhsa_user_sgpr_kernarg_preload_length 0
		.amdhsa_user_sgpr_kernarg_preload_offset 0
		.amdhsa_user_sgpr_private_segment_size 0
		.amdhsa_uses_dynamic_stack 0
		.amdhsa_enable_private_segment 0
		.amdhsa_system_sgpr_workgroup_id_x 1
		.amdhsa_system_sgpr_workgroup_id_y 0
		.amdhsa_system_sgpr_workgroup_id_z 0
		.amdhsa_system_sgpr_workgroup_info 0
		.amdhsa_system_vgpr_workitem_id 0
		.amdhsa_next_free_vgpr 256
		.amdhsa_next_free_sgpr 100
		.amdhsa_accum_offset 256
		.amdhsa_reserve_vcc 1
		.amdhsa_float_round_mode_32 0
		.amdhsa_float_round_mode_16_64 0
		.amdhsa_float_denorm_mode_32 3
		.amdhsa_float_denorm_mode_16_64 3
		.amdhsa_dx10_clamp 1
		.amdhsa_ieee_mode 1
		.amdhsa_fp16_overflow 0
		.amdhsa_tg_split 0
		.amdhsa_exception_fp_ieee_invalid_op 0
		.amdhsa_exception_fp_denorm_src 0
		.amdhsa_exception_fp_ieee_div_zero 0
		.amdhsa_exception_fp_ieee_overflow 0
		.amdhsa_exception_fp_ieee_underflow 0
		.amdhsa_exception_fp_ieee_inexact 0
		.amdhsa_exception_int_div_zero 0
	.end_amdhsa_kernel

; __global__ void __launch_bounds__(512, 2) hymba_fwd(Args args) {
amdhsa.kernels:
  - .agpr_count:     0
    .args:
      - .offset:         0
        .size:           160
        .value_kind:     by_value
      - .offset:         160
        .size:           4
        .value_kind:     hidden_block_count_x
      - .offset:         164
        .size:           4
        .value_kind:     hidden_block_count_y
      - .offset:         168
        .size:           4
        .value_kind:     hidden_block_count_z
      - .offset:         172
        .size:           2
        .value_kind:     hidden_group_size_x
      - .offset:         174
        .size:           2
        .value_kind:     hidden_group_size_y
      - .offset:         176
        .size:           2
        .value_kind:     hidden_group_size_z
      - .offset:         178
        .size:           2
        .value_kind:     hidden_remainder_x
      - .offset:         180
        .size:           2
        .value_kind:     hidden_remainder_y
      - .offset:         182
        .size:           2
        .value_kind:     hidden_remainder_z
      - .offset:         200
        .size:           8
        .value_kind:     hidden_global_offset_x
      - .offset:         208
        .size:           8
        .value_kind:     hidden_global_offset_y
      - .offset:         216
        .size:           8
        .value_kind:     hidden_global_offset_z
      - .offset:         224
        .size:           2
        .value_kind:     hidden_grid_dims
      - .offset:         280
        .size:           4
        .value_kind:     hidden_dynamic_lds_size
    .group_segment_fixed_size: 0
    .kernarg_segment_align: 8
    .kernarg_segment_size: 416
    .language:       OpenCL C
    .language_version:
      - 2
      - 0
    .max_flat_workgroup_size: 512
    .name:           _Z9hymba_fwd4Args
    .private_segment_fixed_size: 0
    .sgpr_count:     106
    .sgpr_spill_count: 44
    .symbol:         _Z9hymba_fwd4Args.kd
    .uniform_work_group_size: 1
    .uses_dynamic_stack: false
    .vgpr_count:     256
    .vgpr_spill_count: 0
    .wavefront_size: 64
